# nt hints also on ROW1/ROW2 residual-stream stores, the prompt-retention K/V loads and the PA/PR gate loads
# baseline (speedup 1.0000x reference)
.LBB0_737:
	s_or_b64 exec, exec, s[4:5]
	v_lshrrev_b32_e32 v32, 3, v134
	v_lshlrev_b32_e32 v134, 2, v132
	v_lshl_add_u64 v[2:3], v[0:1], 0, v[134:135]
	v_lshlrev_b32_e32 v162, 2, v142
	v_mov_b32_e32 v163, v135
	global_load_dwordx4 v[24:27], v[2:3], off
	global_load_dwordx4 v[20:23], v[2:3], off offset:1024
	global_load_dwordx4 v[16:19], v[2:3], off offset:2048
	global_load_dwordx4 v[12:15], v[2:3], off offset:3072
	v_lshl_add_u64 v[2:3], v[0:1], 0, v[162:163]
	v_lshlrev_b32_e32 v160, 2, v144
	v_mov_b32_e32 v161, v135
	v_lshlrev_b32_e32 v158, 2, v146
	v_mov_b32_e32 v159, v135
	v_lshlrev_b32_e32 v156, 2, v148
	v_mov_b32_e32 v157, v135
	v_lshl_add_u64 v[4:5], v[0:1], 0, v[160:161]
	global_load_dwordx4 v[28:31], v[2:3], off
	global_load_dwordx4 v[8:11], v[4:5], off
	v_lshl_add_u64 v[2:3], v[0:1], 0, v[158:159]
	v_lshl_add_u64 v[0:1], v[0:1], 0, v[156:157]
	global_load_dwordx4 v[4:7], v[2:3], off
	s_nop 0
	global_load_dwordx4 v[0:3], v[0:1], off
	v_ashrrev_i32_e32 v33, 12, v130
	v_add_u32_e32 v32, 2, v32
	v_cndmask_b32_e32 v34, v32, v33, vcc
	v_mov_b64_e32 v[32:33], s[8:9]
	v_mad_i64_i32 v[64:65], s[4:5], v34, s58, v[32:33]
	v_lshlrev_b64 v[56:57], 11, v[154:155]
	v_or_b32_e32 v32, v56, v132
	v_mov_b32_e32 v33, v57
	v_lshlrev_b64 v[32:33], 1, v[32:33]
	v_lshl_add_u64 v[34:35], s[10:11], 0, v[32:33]
	v_lshl_add_u64 v[36:37], s[14:15], 0, v[32:33]
	v_lshl_add_u64 v[38:39], s[12:13], 0, v[32:33]
	v_lshl_add_u64 v[32:33], s[26:27], 0, v[32:33]
	global_load_dwordx2 v[100:101], v[34:35], off nt
	global_load_dwordx2 v[102:103], v[36:37], off nt
	global_load_dwordx2 v[104:105], v[38:39], off nt
	global_load_dwordx2 v[106:107], v[32:33], off nt
	v_or_b32_e32 v34, v56, v136
	v_mov_b32_e32 v35, v57
	v_lshl_add_u64 v[58:59], v[64:65], 0, s[52:53]
	v_lshlrev_b64 v[36:37], 1, v[34:35]
	v_lshl_add_u64 v[32:33], v[58:59], 0, v[134:135]
	v_lshl_add_u64 v[38:39], s[10:11], 0, v[36:37]
	global_load_dwordx4 v[32:35], v[32:33], off
	s_nop 0
	global_load_dwordx2 v[108:109], v[38:39], off nt
	v_lshl_add_u64 v[38:39], s[14:15], 0, v[36:37]
	v_lshl_add_u64 v[40:41], s[12:13], 0, v[36:37]
	v_lshl_add_u64 v[36:37], s[26:27], 0, v[36:37]
	global_load_dwordx2 v[110:111], v[38:39], off nt
	global_load_dwordx2 v[112:113], v[40:41], off nt
	global_load_dwordx2 v[114:115], v[36:37], off nt
	v_or_b32_e32 v38, v56, v138
	v_mov_b32_e32 v39, v57
	v_lshlrev_b32_e32 v66, 2, v136
	v_mov_b32_e32 v67, v135
	v_lshlrev_b64 v[40:41], 1, v[38:39]
	v_lshl_add_u64 v[36:37], v[58:59], 0, v[66:67]
	v_lshl_add_u64 v[42:43], s[10:11], 0, v[40:41]
	global_load_dwordx4 v[36:39], v[36:37], off
	s_nop 0
	global_load_dwordx2 v[116:117], v[42:43], off nt
	v_lshl_add_u64 v[42:43], s[14:15], 0, v[40:41]
	v_lshl_add_u64 v[44:45], s[12:13], 0, v[40:41]
	v_lshl_add_u64 v[40:41], s[26:27], 0, v[40:41]
	global_load_dwordx2 v[118:119], v[42:43], off nt
	global_load_dwordx2 v[120:121], v[44:45], off nt
	global_load_dwordx2 v[122:123], v[40:41], off nt
	v_or_b32_e32 v42, v56, v140
	v_mov_b32_e32 v43, v57
	v_lshlrev_b32_e32 v68, 2, v138
	v_mov_b32_e32 v69, v135
	v_lshlrev_b64 v[44:45], 1, v[42:43]
	v_lshl_add_u64 v[40:41], v[58:59], 0, v[68:69]
	v_lshl_add_u64 v[46:47], s[10:11], 0, v[44:45]
	global_load_dwordx4 v[40:43], v[40:41], off
	s_nop 0
	global_load_dwordx2 v[124:125], v[46:47], off nt
	v_lshl_add_u64 v[46:47], s[14:15], 0, v[44:45]
	v_lshl_add_u64 v[48:49], s[12:13], 0, v[44:45]
	v_lshl_add_u64 v[44:45], s[26:27], 0, v[44:45]
	global_load_dwordx2 v[126:127], v[46:47], off nt
	global_load_dwordx2 v[180:181], v[48:49], off nt
	global_load_dwordx2 v[182:183], v[44:45], off nt
	v_or_b32_e32 v46, v56, v142
	v_mov_b32_e32 v47, v57
	v_lshlrev_b32_e32 v70, 2, v140
	v_mov_b32_e32 v71, v135
	v_lshlrev_b64 v[48:49], 1, v[46:47]
	v_lshl_add_u64 v[44:45], v[58:59], 0, v[70:71]
	v_lshl_add_u64 v[50:51], s[10:11], 0, v[48:49]
	global_load_dwordx4 v[44:47], v[44:45], off
	s_nop 0
	global_load_dwordx2 v[184:185], v[50:51], off nt
	v_lshl_add_u64 v[50:51], s[14:15], 0, v[48:49]
	v_lshl_add_u64 v[52:53], s[12:13], 0, v[48:49]
	v_lshl_add_u64 v[48:49], s[26:27], 0, v[48:49]
	global_load_dwordx2 v[186:187], v[50:51], off nt
	global_load_dwordx2 v[98:99], v[52:53], off nt
	global_load_dwordx2 v[96:97], v[48:49], off nt
	v_or_b32_e32 v50, v56, v144
	v_mov_b32_e32 v51, v57
	v_lshlrev_b64 v[52:53], 1, v[50:51]
	v_lshl_add_u64 v[48:49], v[58:59], 0, v[162:163]
	v_lshl_add_u64 v[54:55], s[10:11], 0, v[52:53]
	global_load_dwordx4 v[48:51], v[48:49], off
	s_nop 0
	global_load_dwordx2 v[92:93], v[54:55], off nt
	v_lshl_add_u64 v[54:55], s[14:15], 0, v[52:53]
	v_lshl_add_u64 v[60:61], s[12:13], 0, v[52:53]
	v_lshl_add_u64 v[52:53], s[26:27], 0, v[52:53]
	global_load_dwordx2 v[94:95], v[54:55], off nt
	global_load_dwordx2 v[90:91], v[60:61], off nt
	global_load_dwordx2 v[88:89], v[52:53], off nt
	v_or_b32_e32 v54, v56, v146
	v_mov_b32_e32 v55, v57
	v_lshlrev_b64 v[60:61], 1, v[54:55]
	v_lshl_add_u64 v[52:53], v[58:59], 0, v[160:161]
	v_lshl_add_u64 v[62:63], s[10:11], 0, v[60:61]
	v_or_b32_e32 v56, v56, v148
	global_load_dwordx4 v[52:55], v[52:53], off
	s_nop 0
	global_load_dwordx2 v[84:85], v[62:63], off nt
	v_lshl_add_u64 v[62:63], s[14:15], 0, v[60:61]
	v_lshl_add_u64 v[72:73], s[12:13], 0, v[60:61]
	v_lshl_add_u64 v[60:61], s[26:27], 0, v[60:61]
	v_lshlrev_b64 v[56:57], 1, v[56:57]
	global_load_dwordx2 v[86:87], v[62:63], off nt
	global_load_dwordx2 v[82:83], v[72:73], off nt
	global_load_dwordx2 v[80:81], v[60:61], off nt
	v_lshl_add_u64 v[60:61], v[58:59], 0, v[158:159]
	v_lshl_add_u64 v[72:73], s[10:11], 0, v[56:57]
	global_load_dwordx4 v[60:63], v[60:61], off
	s_nop 0
	global_load_dwordx2 v[76:77], v[72:73], off nt
	v_lshl_add_u64 v[72:73], s[14:15], 0, v[56:57]
	v_lshl_add_u64 v[74:75], s[12:13], 0, v[56:57]
	v_lshl_add_u64 v[56:57], s[26:27], 0, v[56:57]
	global_load_dwordx2 v[78:79], v[72:73], off nt
	s_nop 0
	global_load_dwordx2 v[74:75], v[74:75], off nt
	s_nop 0
	global_load_dwordx2 v[72:73], v[56:57], off nt
	v_lshl_add_u64 v[56:57], v[58:59], 0, v[156:157]
	global_load_dwordx4 v[56:59], v[56:57], off
	s_waitcnt vmcnt(39)
	v_lshlrev_b32_e32 v166, 16, v100
	v_and_b32_e32 v167, 0xffff0000, v100
	s_waitcnt vmcnt(38)
	v_lshlrev_b32_e32 v168, 16, v102
	v_and_b32_e32 v169, 0xffff0000, v102
	v_lshlrev_b32_e32 v100, 16, v101
	v_and_b32_e32 v101, 0xffff0000, v101
	v_lshlrev_b32_e32 v102, 16, v103
	v_and_b32_e32 v103, 0xffff0000, v103
	v_pk_add_f32 v[166:167], v[166:167], v[168:169]
	s_waitcnt vmcnt(37)
	v_lshlrev_b32_e32 v168, 16, v104
	v_and_b32_e32 v169, 0xffff0000, v104
	s_waitcnt vmcnt(36)
	v_lshlrev_b32_e32 v170, 16, v106
	v_and_b32_e32 v171, 0xffff0000, v106
	v_pk_add_f32 v[100:101], v[100:101], v[102:103]
	v_lshlrev_b32_e32 v102, 16, v105
	v_and_b32_e32 v103, 0xffff0000, v105
	v_lshlrev_b32_e32 v104, 16, v107
	v_and_b32_e32 v105, 0xffff0000, v107
	v_pk_add_f32 v[168:169], v[168:169], v[170:171]
	v_pk_add_f32 v[102:103], v[102:103], v[104:105]
	v_pk_add_f32 v[166:167], v[166:167], v[168:169]
	v_pk_add_f32 v[168:169], v[100:101], v[102:103]
	s_waitcnt vmcnt(34)
	v_lshlrev_b32_e32 v100, 16, v108
	v_and_b32_e32 v101, 0xffff0000, v108
	s_waitcnt vmcnt(33)
	v_lshlrev_b32_e32 v102, 16, v110
	v_and_b32_e32 v103, 0xffff0000, v110
	v_pk_add_f32 v[100:101], v[100:101], v[102:103]
	s_waitcnt vmcnt(32)
	v_lshlrev_b32_e32 v102, 16, v112
	v_and_b32_e32 v103, 0xffff0000, v112
	s_waitcnt vmcnt(31)
	v_lshlrev_b32_e32 v104, 16, v114
	v_and_b32_e32 v105, 0xffff0000, v114
	v_pk_add_f32 v[102:103], v[102:103], v[104:105]
	v_lshlrev_b32_e32 v104, 16, v115
	v_pk_add_f32 v[170:171], v[100:101], v[102:103]
	v_lshlrev_b32_e32 v100, 16, v109
	v_and_b32_e32 v101, 0xffff0000, v109
	v_lshlrev_b32_e32 v102, 16, v111
	v_and_b32_e32 v103, 0xffff0000, v111
	v_pk_add_f32 v[100:101], v[100:101], v[102:103]
	v_lshlrev_b32_e32 v102, 16, v113
	v_and_b32_e32 v103, 0xffff0000, v113
	v_and_b32_e32 v105, 0xffff0000, v115
	v_pk_add_f32 v[102:103], v[102:103], v[104:105]
	s_waitcnt vmcnt(26)
	v_lshlrev_b32_e32 v104, 16, v122
	v_pk_add_f32 v[172:173], v[100:101], v[102:103]
	v_lshlrev_b32_e32 v100, 16, v116
	v_and_b32_e32 v101, 0xffff0000, v116
	v_lshlrev_b32_e32 v102, 16, v118
	v_and_b32_e32 v103, 0xffff0000, v118
	v_pk_add_f32 v[100:101], v[100:101], v[102:103]
	v_lshlrev_b32_e32 v102, 16, v120
	v_and_b32_e32 v103, 0xffff0000, v120
	v_and_b32_e32 v105, 0xffff0000, v122
	v_pk_add_f32 v[102:103], v[102:103], v[104:105]
	v_lshlrev_b32_e32 v104, 16, v123
	v_pk_add_f32 v[174:175], v[100:101], v[102:103]
	v_lshlrev_b32_e32 v100, 16, v117
	v_and_b32_e32 v101, 0xffff0000, v117
	v_lshlrev_b32_e32 v102, 16, v119
	v_and_b32_e32 v103, 0xffff0000, v119
	v_pk_add_f32 v[100:101], v[100:101], v[102:103]
	v_lshlrev_b32_e32 v102, 16, v121
	v_and_b32_e32 v103, 0xffff0000, v121
	v_and_b32_e32 v105, 0xffff0000, v123
	v_pk_add_f32 v[102:103], v[102:103], v[104:105]
	s_waitcnt vmcnt(21)
	v_lshlrev_b32_e32 v104, 16, v182
	v_pk_add_f32 v[176:177], v[100:101], v[102:103]
	v_mov_b32_e32 v102, v175
	v_mov_b32_e32 v103, v177
	v_mov_b32_e32 v100, v174
	v_mov_b32_e32 v101, v176
	v_pk_mul_f32 v[102:103], v[102:103], v[102:103]
	v_and_b32_e32 v105, 0xffff0000, v182
	v_pk_fma_f32 v[100:101], v[100:101], v[100:101], v[102:103]
	v_lshlrev_b32_e32 v102, 16, v126
	v_pk_add_f32 v[192:193], v[100:101], v[100:101] op_sel:[0,1] op_sel_hi:[1,0]
	v_lshlrev_b32_e32 v100, 16, v124
	v_and_b32_e32 v101, 0xffff0000, v124
	v_and_b32_e32 v103, 0xffff0000, v126
	v_pk_add_f32 v[100:101], v[100:101], v[102:103]
	v_lshlrev_b32_e32 v102, 16, v180
	v_and_b32_e32 v103, 0xffff0000, v180
	v_pk_add_f32 v[102:103], v[102:103], v[104:105]
	v_lshlrev_b32_e32 v104, 16, v183
	v_pk_add_f32 v[178:179], v[100:101], v[102:103]
	v_lshlrev_b32_e32 v100, 16, v125
	v_and_b32_e32 v101, 0xffff0000, v125
	v_lshlrev_b32_e32 v102, 16, v127
	v_and_b32_e32 v103, 0xffff0000, v127
	v_pk_add_f32 v[100:101], v[100:101], v[102:103]
	v_lshlrev_b32_e32 v102, 16, v181
	v_and_b32_e32 v103, 0xffff0000, v181
	v_and_b32_e32 v105, 0xffff0000, v183
	v_pk_add_f32 v[102:103], v[102:103], v[104:105]
	s_waitcnt vmcnt(16)
	v_lshlrev_b32_e32 v104, 16, v96
	v_pk_add_f32 v[180:181], v[100:101], v[102:103]
	v_mul_f32_e32 v100, v179, v179
	v_pk_fma_f32 v[198:199], v[178:179], v[178:179], v[100:101] op_sel_hi:[1,1,0]
	v_mul_f32_e32 v100, v181, v181
	v_pk_fma_f32 v[200:201], v[180:181], v[180:181], v[100:101] op_sel_hi:[1,1,0]
	v_lshlrev_b32_e32 v100, 16, v184
	v_and_b32_e32 v101, 0xffff0000, v184
	v_lshlrev_b32_e32 v102, 16, v186
	v_and_b32_e32 v103, 0xffff0000, v186
	v_pk_add_f32 v[100:101], v[100:101], v[102:103]
	v_lshlrev_b32_e32 v102, 16, v98
	v_and_b32_e32 v103, 0xffff0000, v98
	v_and_b32_e32 v105, 0xffff0000, v96
	v_pk_add_f32 v[102:103], v[102:103], v[104:105]
	v_lshlrev_b32_e32 v98, 16, v99
	v_pk_add_f32 v[182:183], v[100:101], v[102:103]
	v_lshlrev_b32_e32 v100, 16, v185
	v_and_b32_e32 v101, 0xffff0000, v185
	v_lshlrev_b32_e32 v102, 16, v187
	v_and_b32_e32 v103, 0xffff0000, v187
	v_and_b32_e32 v99, 0xffff0000, v99
	v_lshlrev_b32_e32 v96, 16, v97
	v_and_b32_e32 v97, 0xffff0000, v97
	v_pk_add_f32 v[100:101], v[100:101], v[102:103]
	v_pk_add_f32 v[96:97], v[98:99], v[96:97]
	s_waitcnt vmcnt(13)
	v_lshlrev_b32_e32 v98, 16, v94
	v_pk_add_f32 v[184:185], v[100:101], v[96:97]
	v_lshlrev_b32_e32 v96, 16, v92
	v_and_b32_e32 v97, 0xffff0000, v92
	v_and_b32_e32 v99, 0xffff0000, v94
	v_pk_add_f32 v[96:97], v[96:97], v[98:99]
	s_waitcnt vmcnt(12)
	v_lshlrev_b32_e32 v98, 16, v90
	v_and_b32_e32 v99, 0xffff0000, v90
	s_waitcnt vmcnt(11)
	v_lshlrev_b32_e32 v100, 16, v88
	v_and_b32_e32 v101, 0xffff0000, v88
	v_lshlrev_b32_e32 v92, 16, v93
	v_and_b32_e32 v93, 0xffff0000, v93
	v_lshlrev_b32_e32 v94, 16, v95
	v_and_b32_e32 v95, 0xffff0000, v95
	v_lshlrev_b32_e32 v90, 16, v91
	v_and_b32_e32 v91, 0xffff0000, v91
	v_lshlrev_b32_e32 v88, 16, v89
	v_and_b32_e32 v89, 0xffff0000, v89
	v_pk_add_f32 v[98:99], v[98:99], v[100:101]
	v_pk_add_f32 v[92:93], v[92:93], v[94:95]
	v_pk_add_f32 v[88:89], v[90:91], v[88:89]
	v_pk_add_f32 v[186:187], v[96:97], v[98:99]
	v_pk_add_f32 v[188:189], v[92:93], v[88:89]
	v_mov_b32_e32 v90, v187
	v_mov_b32_e32 v91, v189
	v_mov_b32_e32 v88, v186
	v_mov_b32_e32 v89, v188
	v_pk_mul_f32 v[90:91], v[90:91], v[90:91]
	s_waitcnt vmcnt(6)
	v_lshlrev_b32_e32 v92, 16, v80
	v_pk_fma_f32 v[88:89], v[88:89], v[88:89], v[90:91]
	v_lshlrev_b32_e32 v90, 16, v86
	v_pk_add_f32 v[206:207], v[88:89], v[88:89] op_sel:[0,1] op_sel_hi:[1,0]
	v_lshlrev_b32_e32 v88, 16, v84
	v_and_b32_e32 v89, 0xffff0000, v84
	v_and_b32_e32 v91, 0xffff0000, v86
	v_pk_add_f32 v[88:89], v[88:89], v[90:91]
	v_lshlrev_b32_e32 v90, 16, v82
	v_and_b32_e32 v91, 0xffff0000, v82
	v_and_b32_e32 v93, 0xffff0000, v80
	v_pk_add_f32 v[90:91], v[90:91], v[92:93]
	v_lshlrev_b32_e32 v84, 16, v85
	v_and_b32_e32 v85, 0xffff0000, v85
	v_lshlrev_b32_e32 v86, 16, v87
	v_and_b32_e32 v87, 0xffff0000, v87
	v_lshlrev_b32_e32 v82, 16, v83
	v_and_b32_e32 v83, 0xffff0000, v83
	v_lshlrev_b32_e32 v80, 16, v81
	v_and_b32_e32 v81, 0xffff0000, v81
	v_pk_add_f32 v[190:191], v[88:89], v[90:91]
	v_pk_add_f32 v[84:85], v[84:85], v[86:87]
	v_pk_add_f32 v[80:81], v[82:83], v[80:81]
	s_waitcnt vmcnt(3)
	v_lshlrev_b32_e32 v82, 16, v78
	v_pk_add_f32 v[194:195], v[84:85], v[80:81]
	v_mul_f32_e32 v80, v191, v191
	v_pk_fma_f32 v[208:209], v[190:191], v[190:191], v[80:81] op_sel_hi:[1,1,0]
	v_mul_f32_e32 v80, v195, v195
	v_pk_fma_f32 v[210:211], v[194:195], v[194:195], v[80:81] op_sel_hi:[1,1,0]
	v_lshlrev_b32_e32 v80, 16, v76
	v_and_b32_e32 v81, 0xffff0000, v76
	v_and_b32_e32 v83, 0xffff0000, v78
	v_pk_add_f32 v[80:81], v[80:81], v[82:83]
	s_waitcnt vmcnt(2)
	v_lshlrev_b32_e32 v82, 16, v74
	v_and_b32_e32 v83, 0xffff0000, v74
	s_waitcnt vmcnt(1)
	v_lshlrev_b32_e32 v84, 16, v72
	v_and_b32_e32 v85, 0xffff0000, v72
	v_lshlrev_b32_e32 v76, 16, v77
	v_and_b32_e32 v77, 0xffff0000, v77
	v_lshlrev_b32_e32 v78, 16, v79
	v_and_b32_e32 v79, 0xffff0000, v79
	v_lshlrev_b32_e32 v74, 16, v75
	v_and_b32_e32 v75, 0xffff0000, v75
	v_lshlrev_b32_e32 v72, 16, v73
	v_and_b32_e32 v73, 0xffff0000, v73
	v_pk_add_f32 v[82:83], v[82:83], v[84:85]
	v_pk_add_f32 v[76:77], v[76:77], v[78:79]
	v_pk_add_f32 v[72:73], v[74:75], v[72:73]
	v_pk_add_f32 v[196:197], v[80:81], v[82:83]
	v_pk_add_f32 v[212:213], v[76:77], v[72:73]
	v_pk_mul_f32 v[202:203], v[182:183], v[182:183]
	v_pk_mul_f32 v[204:205], v[184:185], v[184:185]
	v_pk_mul_f32 v[214:215], v[196:197], v[196:197]
	v_pk_mul_f32 v[216:217], v[212:213], v[212:213]
	v_lshl_add_u64 v[218:219], v[64:65], 0, s[54:55]
	v_lshl_add_u64 v[64:65], v[64:65], 0, s[56:57]
	v_lshl_add_u64 v[72:73], v[218:219], 0, v[134:135]
	v_lshl_add_u64 v[74:75], v[64:65], 0, v[134:135]
	global_load_dwordx4 v[120:123], v[72:73], off
	global_load_dwordx4 v[124:127], v[74:75], off
	v_lshl_add_u64 v[72:73], v[218:219], 0, v[66:67]
	v_lshl_add_u64 v[66:67], v[64:65], 0, v[66:67]
	global_load_dwordx4 v[112:115], v[72:73], off
	global_load_dwordx4 v[116:119], v[66:67], off
	v_lshl_add_u64 v[66:67], v[218:219], 0, v[68:69]
	v_lshl_add_u64 v[68:69], v[64:65], 0, v[68:69]
	global_load_dwordx4 v[104:107], v[66:67], off
	global_load_dwordx4 v[108:111], v[68:69], off
	v_lshl_add_u64 v[66:67], v[218:219], 0, v[70:71]
	v_lshl_add_u64 v[68:69], v[64:65], 0, v[70:71]
	global_load_dwordx4 v[96:99], v[66:67], off
	global_load_dwordx4 v[100:103], v[68:69], off
	v_lshl_add_u64 v[66:67], v[218:219], 0, v[162:163]
	v_lshl_add_u64 v[68:69], v[64:65], 0, v[162:163]
	global_load_dwordx4 v[88:91], v[66:67], off
	global_load_dwordx4 v[92:95], v[68:69], off
	v_lshl_add_u64 v[66:67], v[218:219], 0, v[160:161]
	v_lshl_add_u64 v[68:69], v[64:65], 0, v[160:161]
	global_load_dwordx4 v[80:83], v[66:67], off
	global_load_dwordx4 v[84:87], v[68:69], off
	v_lshl_add_u64 v[66:67], v[218:219], 0, v[158:159]
	v_lshl_add_u64 v[68:69], v[64:65], 0, v[158:159]
	global_load_dwordx4 v[72:75], v[66:67], off
	global_load_dwordx4 v[76:79], v[68:69], off
	v_lshl_add_u64 v[66:67], v[218:219], 0, v[156:157]
	v_lshl_add_u64 v[68:69], v[64:65], 0, v[156:157]
	global_load_dwordx4 v[64:67], v[66:67], off
	s_nop 0
	global_load_dwordx4 v[68:71], v[68:69], off
	v_mov_b32_e32 v222, v169
	v_mov_b32_e32 v223, v173
	v_mov_b32_e32 v218, v167
	v_mov_b32_e32 v219, v171
	v_mov_b32_e32 v220, v168
	v_mov_b32_e32 v221, v172
	v_pk_mul_f32 v[222:223], v[222:223], v[222:223]
	v_pk_mul_f32 v[218:219], v[218:219], v[218:219]
	v_pk_fma_f32 v[220:221], v[220:221], v[220:221], v[222:223]
	v_mov_b32_e32 v222, v166
	v_mov_b32_e32 v223, v170
	v_pk_fma_f32 v[218:219], v[222:223], v[222:223], v[218:219]
	v_mov_b32_e32 v199, v204
	v_pk_add_f32 v[218:219], v[218:219], v[220:221]
	v_mov_b32_e32 v201, v205
	v_pk_add_f32 v[218:219], v[218:219], v[218:219] op_sel:[0,1] op_sel_hi:[1,0]
	v_mov_b32_e32 v193, v203
	v_mov_b32_e32 v219, v202
	v_pk_add_f32 v[198:199], v[198:199], v[200:201]
	v_pk_add_f32 v[192:193], v[218:219], v[192:193]
	v_mov_b32_e32 v209, v216
	v_pk_add_f32 v[192:193], v[192:193], v[198:199]
	v_mov_b32_e32 v211, v217
	v_pk_add_f32 v[192:193], v[192:193], v[192:193] op_sel:[0,1] op_sel_hi:[1,0]
	v_mov_b32_e32 v207, v215
	v_mov_b32_e32 v193, v214
	v_pk_add_f32 v[198:199], v[208:209], v[210:211]
	v_pk_add_f32 v[192:193], v[192:193], v[206:207]
	s_nop 0
	v_pk_add_f32 v[192:193], v[192:193], v[198:199]
	s_nop 0
	v_add_f32_e32 v147, v192, v193
	ds_bpermute_b32 v149, v129, v147
	v_lshl_add_u64 v[164:165], s[48:49], 0, v[164:165]
	v_lshl_add_u64 v[192:193], v[164:165], 0, v[134:135]
	v_lshl_add_u64 v[162:163], v[164:165], 0, v[162:163]
	s_waitcnt lgkmcnt(0)
	v_add_f32_e32 v147, v147, v149
	ds_bpermute_b32 v149, v133, v147
	s_waitcnt lgkmcnt(0)
	v_add_f32_e32 v147, v147, v149
	ds_bpermute_b32 v149, v137, v147
	s_waitcnt lgkmcnt(0)
	v_add_f32_e32 v147, v147, v149
	ds_bpermute_b32 v149, v139, v147
	s_waitcnt lgkmcnt(0)
	v_add_f32_e32 v147, v147, v149
	ds_bpermute_b32 v149, v141, v147
	s_waitcnt lgkmcnt(0)
	v_add_f32_e32 v147, v147, v149
	ds_bpermute_b32 v149, v143, v147
	s_waitcnt lgkmcnt(0)
	v_add_f32_e32 v147, v147, v149
	v_fmamk_f32 v147, v147, 0x3a000000, v145
	v_mul_f32_e32 v149, 0x4b800000, v147
	v_cmp_gt_f32_e32 vcc, s59, v147
	s_nop 1
	v_cndmask_b32_e32 v147, v147, v149, vcc
	v_rsq_f32_e32 v147, v147
	s_nop 0
	v_mul_f32_e32 v134, 0x45800000, v147
	v_cndmask_b32_e32 v134, v147, v134, vcc
	v_pk_mul_f32 v[166:167], v[166:167], v[134:135] op_sel_hi:[1,0]
	v_pk_mul_f32 v[168:169], v[168:169], v[134:135] op_sel_hi:[1,0]
	v_pk_mul_f32 v[186:187], v[186:187], v[134:135] op_sel_hi:[1,0]
	v_pk_fma_f32 v[24:25], v[32:33], v[166:167], v[24:25]
	v_pk_mul_f32 v[32:33], v[188:189], v[134:135] op_sel_hi:[1,0]
	v_pk_mul_f32 v[170:171], v[170:171], v[134:135] op_sel_hi:[1,0]
	v_pk_mul_f32 v[172:173], v[172:173], v[134:135] op_sel_hi:[1,0]
	v_pk_mul_f32 v[174:175], v[174:175], v[134:135] op_sel_hi:[1,0]
	v_pk_mul_f32 v[176:177], v[176:177], v[134:135] op_sel_hi:[1,0]
	v_pk_mul_f32 v[178:179], v[178:179], v[134:135] op_sel_hi:[1,0]
	v_pk_mul_f32 v[180:181], v[180:181], v[134:135] op_sel_hi:[1,0]
	v_pk_mul_f32 v[182:183], v[182:183], v[134:135] op_sel_hi:[1,0]
	v_pk_mul_f32 v[184:185], v[184:185], v[134:135] op_sel_hi:[1,0]
	v_pk_fma_f32 v[26:27], v[34:35], v[168:169], v[26:27]
	v_pk_fma_f32 v[10:11], v[54:55], v[32:33], v[10:11]
	v_pk_fma_f32 v[8:9], v[52:53], v[186:187], v[8:9]
	v_lshl_add_u64 v[32:33], v[164:165], 0, v[160:161]
	v_pk_fma_f32 v[22:23], v[38:39], v[172:173], v[22:23]
	v_pk_fma_f32 v[20:21], v[36:37], v[170:171], v[20:21]
	v_pk_fma_f32 v[18:19], v[42:43], v[176:177], v[18:19]
	v_pk_fma_f32 v[16:17], v[40:41], v[174:175], v[16:17]
	v_pk_fma_f32 v[14:15], v[46:47], v[180:181], v[14:15]
	v_pk_fma_f32 v[12:13], v[44:45], v[178:179], v[12:13]
	v_pk_fma_f32 v[30:31], v[50:51], v[184:185], v[30:31]
	v_pk_fma_f32 v[28:29], v[48:49], v[182:183], v[28:29]
	global_store_dwordx4 v[192:193], v[24:27], off nt
	global_store_dwordx4 v[192:193], v[20:23], off offset:1024 nt
	global_store_dwordx4 v[192:193], v[16:19], off offset:2048 nt
	global_store_dwordx4 v[192:193], v[12:15], off offset:3072 nt
	global_store_dwordx4 v[162:163], v[28:31], off nt
	global_store_dwordx4 v[32:33], v[8:11], off nt
	v_pk_mul_f32 v[32:33], v[190:191], v[134:135] op_sel_hi:[1,0]
	v_pk_mul_f32 v[34:35], v[194:195], v[134:135] op_sel_hi:[1,0]
	v_pk_fma_f32 v[4:5], v[60:61], v[32:33], v[4:5]
	v_pk_fma_f32 v[6:7], v[62:63], v[34:35], v[6:7]
	v_lshl_add_u64 v[32:33], v[164:165], 0, v[158:159]
	global_store_dwordx4 v[32:33], v[4:7], off nt
	v_pk_mul_f32 v[32:33], v[196:197], v[134:135] op_sel_hi:[1,0]
	v_pk_mul_f32 v[34:35], v[212:213], v[134:135] op_sel_hi:[1,0]
	s_waitcnt vmcnt(23)
	v_pk_fma_f32 v[0:1], v[56:57], v[32:33], v[0:1]
	v_pk_fma_f32 v[2:3], v[58:59], v[34:35], v[2:3]
	v_lshl_add_u64 v[32:33], v[164:165], 0, v[156:157]
	global_store_dwordx4 v[32:33], v[0:3], off nt
	v_mov_b32_e32 v34, v25
	v_mov_b32_e32 v35, v21
	v_mov_b32_e32 v32, v24
	v_mov_b32_e32 v33, v20
	v_pk_mul_f32 v[34:35], v[34:35], v[34:35]
	v_mov_b32_e32 v36, v27
	v_mov_b32_e32 v37, v23
	v_pk_fma_f32 v[32:33], v[32:33], v[32:33], v[34:35]
	v_mov_b32_e32 v34, v26
	v_mov_b32_e32 v35, v22
	v_pk_mul_f32 v[36:37], v[36:37], v[36:37]
	v_readfirstlane_b32 s83, v237
	s_lshl_b32 s83, s83, 1
	s_add_u32 s83, s83, s86
	s_add_u32 s83, s83, s94
	s_lshl_b32 s83, s83, 3
	s_sub_u32 s84, s83, s82
	s_mov_b32 s82, s83
	s_mov_b32 s85, 0
	s_mov_b64 s[6:7], s[84:85]
	s_lshl_b64 s[28:29], s[84:85], 13
	v_lshl_add_u64 v[130:131], v[130:131], 0, s[6:7]
	v_pk_fma_f32 v[34:35], v[34:35], v[34:35], v[36:37]
	v_pk_mul_f32 v[36:37], v[16:17], v[16:17]
	v_pk_add_f32 v[32:33], v[32:33], v[34:35]
	v_pk_mul_f32 v[34:35], v[18:19], v[18:19]
	v_pk_add_f32 v[32:33], v[32:33], v[32:33] op_sel_hi:[0,1]
	v_pk_mov_b32 v[38:39], v[36:37], v[34:35] op_sel:[1,0]
	v_mov_b32_e32 v37, v35
	v_mul_f32_e32 v32, v12, v12
	v_pk_add_f32 v[34:35], v[38:39], v[36:37]
	v_pk_fma_f32 v[36:37], v[12:13], v[12:13], v[32:33] op_sel_hi:[1,1,0]
	v_mul_f32_e32 v32, v14, v14
	v_pk_add_f32 v[34:35], v[34:35], v[34:35] op_sel_hi:[0,1]
	v_pk_fma_f32 v[38:39], v[14:15], v[14:15], v[32:33] op_sel_hi:[1,1,0]
	v_mul_f32_e32 v36, v28, v28
	v_mul_f32_e32 v38, v29, v29
	v_mul_f32_e32 v34, v30, v30
	v_mul_f32_e32 v32, v31, v31
	v_pk_add_f32 v[36:37], v[36:37], v[38:39]
	v_pk_add_f32 v[32:33], v[34:35], v[32:33]
	v_pk_mul_f32 v[34:35], v[10:11], v[10:11]
	v_pk_add_f32 v[32:33], v[36:37], v[32:33]
	v_pk_mul_f32 v[36:37], v[8:9], v[8:9]
	v_pk_add_f32 v[32:33], v[32:33], v[32:33] op_sel_hi:[0,1]
	v_pk_mov_b32 v[38:39], v[36:37], v[34:35] op_sel:[1,0]
	v_mov_b32_e32 v37, v35
	v_mul_f32_e32 v32, v4, v4
	v_pk_add_f32 v[34:35], v[38:39], v[36:37]
	v_pk_fma_f32 v[36:37], v[4:5], v[4:5], v[32:33] op_sel_hi:[1,1,0]
	v_mul_f32_e32 v32, v6, v6
	v_pk_add_f32 v[34:35], v[34:35], v[34:35] op_sel_hi:[0,1]
	v_pk_fma_f32 v[38:39], v[6:7], v[6:7], v[32:33] op_sel_hi:[1,1,0]
	v_mul_f32_e32 v36, v0, v0
	v_mul_f32_e32 v38, v1, v1
	v_mul_f32_e32 v34, v2, v2
	v_mul_f32_e32 v32, v3, v3
	v_pk_add_f32 v[36:37], v[36:37], v[38:39]
	v_pk_add_f32 v[32:33], v[34:35], v[32:33]
	v_lshlrev_b64 v[34:35], 12, v[154:155]
	v_pk_add_f32 v[32:33], v[36:37], v[32:33]
	v_lshl_add_u64 v[152:153], v[152:153], 0, s[28:29]
	v_add_f32_e32 v32, v32, v33
	ds_bpermute_b32 v33, v129, v32
	s_waitcnt lgkmcnt(0)
	v_add_f32_e32 v32, v32, v33
	ds_bpermute_b32 v33, v133, v32
	s_waitcnt lgkmcnt(0)
	v_add_f32_e32 v32, v32, v33
	ds_bpermute_b32 v33, v137, v32
	s_waitcnt lgkmcnt(0)
	v_add_f32_e32 v32, v32, v33
	ds_bpermute_b32 v33, v139, v32
	s_waitcnt lgkmcnt(0)
	v_add_f32_e32 v32, v32, v33
	ds_bpermute_b32 v33, v141, v32
	s_waitcnt lgkmcnt(0)
	v_add_f32_e32 v32, v32, v33
	ds_bpermute_b32 v33, v143, v32
	s_waitcnt lgkmcnt(0)
	v_add_f32_e32 v32, v32, v33
	v_fmamk_f32 v32, v32, 0x3a000000, v145
	v_mul_f32_e32 v33, 0x4b800000, v32
	v_cmp_gt_f32_e32 vcc, s59, v32
	s_nop 1
	v_cndmask_b32_e32 v32, v32, v33, vcc
	v_rsq_f32_e32 v32, v32
	s_nop 0
	v_mul_f32_e32 v33, 0x45800000, v32
	v_cndmask_b32_e32 v32, v32, v33, vcc
	v_pk_mul_f32 v[24:25], v[24:25], v[32:33] op_sel_hi:[1,0]
	v_pk_mul_f32 v[26:27], v[26:27], v[32:33] op_sel_hi:[1,0]
	v_pk_mul_f32 v[12:13], v[12:13], v[32:33] op_sel_hi:[1,0]
	v_pk_mul_f32 v[14:15], v[14:15], v[32:33] op_sel_hi:[1,0]
	s_waitcnt vmcnt(22)
	v_pk_fma_f32 v[26:27], v[122:123], v[26:27], v[126:127]
	v_pk_fma_f32 v[24:25], v[120:121], v[24:25], v[124:125]
	s_waitcnt vmcnt(16)
	v_pk_fma_f32 v[14:15], v[98:99], v[14:15], v[102:103]
	v_pk_fma_f32 v[12:13], v[96:97], v[12:13], v[100:101]
	v_cvt_pk_bf16_f32 v24, v24, v25
	v_cvt_pk_bf16_f32 v25, v26, v27
	v_lshl_add_u64 v[26:27], v[150:151], 0, v[34:35]
	v_cvt_pk_bf16_f32 v12, v12, v13
	v_cvt_pk_bf16_f32 v13, v14, v15
	v_pk_mul_f32 v[20:21], v[20:21], v[32:33] op_sel_hi:[1,0]
	v_pk_mul_f32 v[22:23], v[22:23], v[32:33] op_sel_hi:[1,0]
	v_pk_mul_f32 v[16:17], v[16:17], v[32:33] op_sel_hi:[1,0]
	v_pk_mul_f32 v[18:19], v[18:19], v[32:33] op_sel_hi:[1,0]
	global_store_dwordx2 v[26:27], v[12:13], off offset:1536
	v_pk_mul_f32 v[12:13], v[28:29], v[32:33] op_sel_hi:[1,0]
	v_pk_mul_f32 v[14:15], v[30:31], v[32:33] op_sel_hi:[1,0]
	v_pk_mul_f32 v[8:9], v[8:9], v[32:33] op_sel_hi:[1,0]
	v_pk_mul_f32 v[10:11], v[10:11], v[32:33] op_sel_hi:[1,0]
	v_pk_mul_f32 v[4:5], v[4:5], v[32:33] op_sel_hi:[1,0]
	v_pk_mul_f32 v[6:7], v[6:7], v[32:33] op_sel_hi:[1,0]
	v_pk_mul_f32 v[0:1], v[0:1], v[32:33] op_sel_hi:[1,0]
	v_pk_mul_f32 v[2:3], v[2:3], v[32:33] op_sel_hi:[1,0]
	v_pk_fma_f32 v[22:23], v[114:115], v[22:23], v[118:119]
	v_pk_fma_f32 v[20:21], v[112:113], v[20:21], v[116:117]
	v_pk_fma_f32 v[18:19], v[106:107], v[18:19], v[110:111]
	v_pk_fma_f32 v[16:17], v[104:105], v[16:17], v[108:109]
	s_waitcnt vmcnt(15)
	v_pk_fma_f32 v[14:15], v[90:91], v[14:15], v[94:95]
	v_pk_fma_f32 v[12:13], v[88:89], v[12:13], v[92:93]
	s_waitcnt vmcnt(13)
	v_pk_fma_f32 v[10:11], v[82:83], v[10:11], v[86:87]
	v_pk_fma_f32 v[8:9], v[80:81], v[8:9], v[84:85]
	s_waitcnt vmcnt(11)
	v_pk_fma_f32 v[6:7], v[74:75], v[6:7], v[78:79]
	v_pk_fma_f32 v[4:5], v[72:73], v[4:5], v[76:77]
	s_waitcnt vmcnt(9)
	v_pk_fma_f32 v[2:3], v[66:67], v[2:3], v[70:71]
	v_pk_fma_f32 v[0:1], v[64:65], v[0:1], v[68:69]
	v_cmp_lt_i32_e32 vcc, s60, v130
	v_cvt_pk_bf16_f32 v20, v20, v21
	v_cvt_pk_bf16_f32 v21, v22, v23
	v_cvt_pk_bf16_f32 v16, v16, v17
	v_cvt_pk_bf16_f32 v17, v18, v19
	v_cvt_pk_bf16_f32 v12, v12, v13
	v_cvt_pk_bf16_f32 v13, v14, v15
	v_cvt_pk_bf16_f32 v8, v8, v9
	v_cvt_pk_bf16_f32 v9, v10, v11
	v_cvt_pk_bf16_f32 v4, v4, v5
	v_cvt_pk_bf16_f32 v5, v6, v7
	v_cvt_pk_bf16_f32 v0, v0, v1
	v_cvt_pk_bf16_f32 v1, v2, v3
	s_or_b64 s[30:31], vcc, s[30:31]
	global_store_dwordx2 v[26:27], v[24:25], off
	global_store_dwordx2 v[26:27], v[20:21], off offset:512
	global_store_dwordx2 v[26:27], v[16:17], off offset:1024
	global_store_dwordx2 v[26:27], v[12:13], off offset:2048
	global_store_dwordx2 v[26:27], v[8:9], off offset:2560
	global_store_dwordx2 v[26:27], v[4:5], off offset:3072
	global_store_dwordx2 v[26:27], v[0:1], off offset:3584
	s_andn2_b64 exec, exec, s[30:31]
	s_cbranch_execz .LBB0_742

.LBB0_973:
	s_bfe_u32 s52, s35, 0x30005
	s_and_b32 s53, s14, 0xfffff000
	s_and_b32 s54, s16, 0xf80
	v_cvt_f32_ubyte0_e32 v30, s52
	s_or_b32 s53, s53, s54
	v_sub_f32_e32 v30, 0xc0a00000, v30
	s_mul_hi_i32 s54, s53, 0x5c00
	s_mulk_i32 s53, 0x5c00
	v_cmp_gt_f32_e32 vcc, s18, v30
	s_add_u32 s53, s12, s53
	s_addc_u32 s58, s13, s54
	v_cndmask_b32_e32 v31, 0, v27, vcc
	s_lshl_b32 s54, s52, 8
	v_add_f32_e32 v30, v30, v31
	s_add_u32 s54, s53, s54
	v_exp_f32_e32 v32, v30
	s_addc_u32 s55, s58, 0
	v_mov_b32_e32 v15, v1
	s_and_b64 s[56:57], vcc, exec
	v_lshl_add_u64 v[30:31], s[54:55], 0, v[0:1]
	s_cselect_b32 s54, 0xffffffc0, 0
	v_lshl_add_u64 v[30:31], v[30:31], 0, v[14:15]
	v_ldexp_f32 v46, v32, s54
	v_lshl_add_u64 v[42:43], v[30:31], 0, s[8:9]
	v_add_co_u32_e32 v30, vcc, s26, v30
	v_sub_f32_e32 v46, 1.0, v46
	s_nop 0
	v_addc_co_u32_e32 v31, vcc, 0, v31, vcc
	v_cmp_gt_f32_e32 vcc, s19, v46
	s_and_b64 s[54:55], vcc, exec
	s_cselect_b32 s54, 32, 0
	s_lshl_b32 s52, s52, 9
	s_add_u32 s52, s53, s52
	v_ldexp_f32 v46, v46, s54
	s_addc_u32 s53, s58, 0
	v_log_f32_e32 v49, v46
	v_lshl_add_u64 v[46:47], s[52:53], 0, v[0:1]
	global_load_dwordx4 v[30:33], v[30:31], off offset:1024 nt
	s_nop 0
	global_load_dwordx4 v[34:37], v[42:43], off offset:64 nt
	global_load_dwordx4 v[38:41], v[42:43], off offset:128 nt
	s_nop 0
	global_load_dwordx4 v[42:45], v[42:43], off offset:192 nt
	v_lshl_add_u64 v[46:47], v[46:47], 0, v[14:15]
	v_cndmask_b32_e32 v48, 0, v28, vcc
	v_add_co_u32_e32 v74, vcc, s26, v46
	v_lshl_add_u64 v[62:63], v[46:47], 0, s[10:11]
	s_nop 0
	v_addc_co_u32_e32 v75, vcc, 0, v47, vcc
	v_sub_f32_e32 v15, v49, v48
	global_load_dwordx4 v[46:49], v[62:63], off offset:64 nt
	global_load_dwordx4 v[50:53], v[62:63], off offset:128 nt
	global_load_dwordx4 v[54:57], v[62:63], off offset:192 nt
	global_load_dwordx4 v[58:61], v[62:63], off offset:256 nt
	global_load_dwordx4 v[66:69], v[62:63], off offset:320 nt
	global_load_dwordx4 v[70:73], v[62:63], off offset:384 nt
	s_nop 0
	global_load_dwordx4 v[74:77], v[74:75], off offset:3072 nt
	s_nop 0
	global_load_dwordx4 v[78:81], v[62:63], off offset:448 nt
	v_mul_f32_e32 v62, v15, v16
	v_cmp_gt_f32_e32 vcc, s18, v62
	s_add_i32 s35, s35, s94
	s_add_i32 s14, s14, s15
	v_cndmask_b32_e32 v62, 0, v27, vcc
	v_fmac_f32_e32 v62, v15, v16
	v_exp_f32_e32 v62, v62
	v_cndmask_b32_e32 v15, 0, v29, vcc
	s_add_i32 s16, s16, s17
	v_lshl_add_u64 v[126:127], s[50:51], 0, v[4:5]
	v_ldexp_f32 v62, v62, v15
	v_lshl_add_u64 v[154:155], s[50:51], 0, v[6:7]
	v_lshl_add_u64 v[156:157], s[50:51], 0, v[8:9]
	v_lshl_add_u64 v[158:159], s[50:51], 0, v[10:11]
	v_lshl_add_u64 v[4:5], v[4:5], 0, s[4:5]
	v_lshl_add_u64 v[6:7], v[6:7], 0, s[4:5]
	v_lshl_add_u64 v[8:9], v[8:9], 0, s[4:5]
	v_lshl_add_u64 v[10:11], v[10:11], 0, s[4:5]
	s_cmpk_gt_i32 s35, 0x1ff
	s_waitcnt vmcnt(11)
	v_lshlrev_b32_e32 v82, 16, v30
	v_and_b32_e32 v83, 0xffff0000, v30
	v_lshlrev_b32_e32 v30, 16, v31
	v_and_b32_e32 v31, 0xffff0000, v31
	v_lshlrev_b32_e32 v84, 16, v32
	v_and_b32_e32 v85, 0xffff0000, v32
	v_lshlrev_b32_e32 v32, 16, v33
	v_and_b32_e32 v33, 0xffff0000, v33
	s_waitcnt vmcnt(10)
	v_lshlrev_b32_e32 v86, 16, v34
	v_and_b32_e32 v87, 0xffff0000, v34
	v_lshlrev_b32_e32 v34, 16, v35
	v_and_b32_e32 v35, 0xffff0000, v35
	v_lshlrev_b32_e32 v88, 16, v36
	v_and_b32_e32 v89, 0xffff0000, v36
	v_lshlrev_b32_e32 v36, 16, v37
	v_and_b32_e32 v37, 0xffff0000, v37
	s_waitcnt vmcnt(9)
	v_lshlrev_b32_e32 v90, 16, v38
	v_and_b32_e32 v91, 0xffff0000, v38
	v_lshlrev_b32_e32 v38, 16, v39
	v_and_b32_e32 v39, 0xffff0000, v39
	v_lshlrev_b32_e32 v92, 16, v40
	v_and_b32_e32 v93, 0xffff0000, v40
	v_lshlrev_b32_e32 v40, 16, v41
	v_and_b32_e32 v41, 0xffff0000, v41
	s_waitcnt vmcnt(8)
	v_lshlrev_b32_e32 v94, 16, v42
	v_and_b32_e32 v95, 0xffff0000, v42
	v_lshlrev_b32_e32 v42, 16, v43
	v_and_b32_e32 v43, 0xffff0000, v43
	v_lshlrev_b32_e32 v96, 16, v44
	v_and_b32_e32 v97, 0xffff0000, v44
	v_lshlrev_b32_e32 v44, 16, v45
	v_and_b32_e32 v45, 0xffff0000, v45
	v_pk_mul_f32 v[82:83], v[62:63], v[82:83] op_sel_hi:[0,1]
	v_pk_mul_f32 v[30:31], v[62:63], v[30:31] op_sel_hi:[0,1]
	v_pk_mul_f32 v[84:85], v[62:63], v[84:85] op_sel_hi:[0,1]
	v_pk_mul_f32 v[32:33], v[62:63], v[32:33] op_sel_hi:[0,1]
	v_pk_mul_f32 v[86:87], v[62:63], v[86:87] op_sel_hi:[0,1]
	v_pk_mul_f32 v[34:35], v[62:63], v[34:35] op_sel_hi:[0,1]
	v_pk_mul_f32 v[88:89], v[62:63], v[88:89] op_sel_hi:[0,1]
	v_pk_mul_f32 v[36:37], v[62:63], v[36:37] op_sel_hi:[0,1]
	v_pk_mul_f32 v[90:91], v[62:63], v[90:91] op_sel_hi:[0,1]
	v_pk_mul_f32 v[38:39], v[62:63], v[38:39] op_sel_hi:[0,1]
	v_pk_mul_f32 v[92:93], v[62:63], v[92:93] op_sel_hi:[0,1]
	v_pk_mul_f32 v[40:41], v[62:63], v[40:41] op_sel_hi:[0,1]
	v_pk_mul_f32 v[94:95], v[62:63], v[94:95] op_sel_hi:[0,1]
	v_pk_mul_f32 v[42:43], v[62:63], v[42:43] op_sel_hi:[0,1]
	v_pk_mul_f32 v[96:97], v[62:63], v[96:97] op_sel_hi:[0,1]
	v_pk_mul_f32 v[44:45], v[62:63], v[44:45] op_sel_hi:[0,1]
	v_cvt_pk_bf16_f32 v15, v82, v83
	v_cvt_pk_bf16_f32 v30, v30, v31
	v_cvt_pk_bf16_f32 v31, v84, v85
	v_cvt_pk_bf16_f32 v32, v32, v33
	v_cvt_pk_bf16_f32 v33, v86, v87
	v_cvt_pk_bf16_f32 v34, v34, v35
	v_cvt_pk_bf16_f32 v35, v88, v89
	v_cvt_pk_bf16_f32 v36, v36, v37
	v_cvt_pk_bf16_f32 v37, v90, v91
	v_cvt_pk_bf16_f32 v38, v38, v39
	v_cvt_pk_bf16_f32 v39, v92, v93
	v_cvt_pk_bf16_f32 v40, v40, v41
	v_cvt_pk_bf16_f32 v41, v94, v95
	v_cvt_pk_bf16_f32 v42, v42, v43
	v_cvt_pk_bf16_f32 v43, v96, v97
	v_cvt_pk_bf16_f32 v44, v44, v45
	ds_write_b16 v18, v15
	ds_write_b16_d16_hi v18, v15 offset:272
	ds_write_b16 v18, v30 offset:544
	ds_write_b16_d16_hi v18, v30 offset:816
	ds_write_b16 v18, v31 offset:1088
	ds_write_b16_d16_hi v18, v31 offset:1360
	ds_write_b16 v18, v32 offset:1632
	ds_write_b16_d16_hi v18, v32 offset:1904
	ds_write_b16 v18, v33 offset:8704
	ds_write_b16_d16_hi v18, v33 offset:8976
	ds_write_b16 v18, v34 offset:9248
	ds_write_b16_d16_hi v18, v34 offset:9520
	ds_write_b16 v18, v35 offset:9792
	ds_write_b16_d16_hi v18, v35 offset:10064
	ds_write_b16 v18, v36 offset:10336
	ds_write_b16_d16_hi v18, v36 offset:10608
	ds_write_b16 v18, v37 offset:17408
	ds_write_b16_d16_hi v18, v37 offset:17680
	ds_write_b16 v18, v38 offset:17952
	ds_write_b16_d16_hi v18, v38 offset:18224
	ds_write_b16 v18, v39 offset:18496
	ds_write_b16_d16_hi v18, v39 offset:18768
	ds_write_b16 v18, v40 offset:19040
	ds_write_b16_d16_hi v18, v40 offset:19312
	ds_write_b16 v18, v41 offset:26112
	ds_write_b16_d16_hi v18, v41 offset:26384
	ds_write_b16 v18, v42 offset:26656
	ds_write_b16_d16_hi v18, v42 offset:26928
	ds_write_b16 v18, v43 offset:27200
	ds_write_b16_d16_hi v18, v43 offset:27472
	ds_write_b16 v18, v44 offset:27744
	ds_write_b16_d16_hi v18, v44 offset:28016
	s_waitcnt vmcnt(1)
	ds_write_b16 v18, v74 offset:34816
	ds_write_b16_d16_hi v18, v74 offset:35088
	ds_write_b16 v18, v75 offset:35360
	ds_write_b16_d16_hi v18, v75 offset:35632
	ds_write_b16 v18, v76 offset:35904
	ds_write_b16_d16_hi v18, v76 offset:36176
	ds_write_b16 v18, v77 offset:36448
	ds_write_b16_d16_hi v18, v77 offset:36720
	ds_write_b16 v18, v46 offset:43520
	ds_write_b16_d16_hi v18, v46 offset:43792
	ds_write_b16 v18, v47 offset:44064
	ds_write_b16_d16_hi v18, v47 offset:44336
	ds_write_b16 v18, v48 offset:44608
	ds_write_b16_d16_hi v18, v48 offset:44880
	ds_write_b16 v18, v49 offset:45152
	ds_write_b16_d16_hi v18, v49 offset:45424
	ds_write_b16 v18, v50 offset:52224
	ds_write_b16_d16_hi v18, v50 offset:52496
	ds_write_b16 v18, v51 offset:52768
	ds_write_b16_d16_hi v18, v51 offset:53040
	ds_write_b16 v18, v52 offset:53312
	ds_write_b16_d16_hi v18, v52 offset:53584
	ds_write_b16 v18, v53 offset:53856
	ds_write_b16_d16_hi v18, v53 offset:54128
	ds_write_b16 v18, v54 offset:60928
	ds_write_b16_d16_hi v18, v54 offset:61200
	ds_write_b16 v18, v55 offset:61472
	ds_write_b16_d16_hi v18, v55 offset:61744
	ds_write_b16 v18, v56 offset:62016
	ds_write_b16_d16_hi v18, v56 offset:62288
	ds_write_b16 v18, v57 offset:62560
	ds_write_b16_d16_hi v18, v57 offset:62832
	ds_write_b16 v19, v58 offset:34816
	ds_write_b16_d16_hi v19, v58 offset:35088
	ds_write_b16 v19, v59 offset:35360
	ds_write_b16_d16_hi v19, v59 offset:35632
	ds_write_b16 v19, v60 offset:35904
	ds_write_b16_d16_hi v19, v60 offset:36176
	ds_write_b16 v19, v61 offset:36448
	ds_write_b16_d16_hi v19, v61 offset:36720
	ds_write_b16 v19, v66 offset:43520
	ds_write_b16_d16_hi v19, v66 offset:43792
	ds_write_b16 v19, v67 offset:44064
	ds_write_b16_d16_hi v19, v67 offset:44336
	ds_write_b16 v19, v68 offset:44608
	ds_write_b16_d16_hi v19, v68 offset:44880
	ds_write_b16 v19, v69 offset:45152
	ds_write_b16_d16_hi v19, v69 offset:45424
	ds_write_b16 v19, v70 offset:52224
	ds_write_b16_d16_hi v19, v70 offset:52496
	ds_write_b16 v19, v71 offset:52768
	ds_write_b16_d16_hi v19, v71 offset:53040
	ds_write_b16 v19, v72 offset:53312
	ds_write_b16_d16_hi v19, v72 offset:53584
	ds_write_b16 v19, v73 offset:53856
	ds_write_b16_d16_hi v19, v73 offset:54128
	s_waitcnt vmcnt(0)
	ds_write_b16 v19, v78 offset:60928
	ds_write_b16_d16_hi v19, v78 offset:61200
	ds_write_b16 v19, v79 offset:61472
	ds_write_b16_d16_hi v19, v79 offset:61744
	ds_write_b16 v19, v80 offset:62016
	ds_write_b16_d16_hi v19, v80 offset:62288
	ds_write_b16 v19, v81 offset:62560
	ds_write_b16_d16_hi v19, v81 offset:62832
	s_waitcnt lgkmcnt(0)
	s_barrier
	ds_read_b128 v[30:33], v26
	ds_read_b128 v[34:37], v17 offset:34816
	ds_read_b128 v[38:41], v17 offset:34880
	ds_read_b128 v[42:45], v26 offset:64
	ds_read_b128 v[50:53], v17 offset:39168
	ds_read_b128 v[54:57], v17 offset:39232
	ds_read_b128 v[58:61], v26 offset:4352
	ds_read_b128 v[66:69], v26 offset:4416
	ds_read_b128 v[74:77], v26 offset:8704
	ds_read_b128 v[78:81], v26 offset:8768
	ds_read_b128 v[86:89], v26 offset:13056
	ds_read_b128 v[90:93], v26 offset:13120
	ds_read_b128 v[98:101], v26 offset:17408
	ds_read_b128 v[102:105], v26 offset:17472
	ds_read_b128 v[110:113], v26 offset:21760
	ds_read_b128 v[114:117], v26 offset:21824
	ds_read_b128 v[122:125], v26 offset:26112
	ds_read_b128 v[130:133], v26 offset:26176
	ds_read_b128 v[138:141], v26 offset:30464
	ds_read_b128 v[142:145], v26 offset:30528
	s_waitcnt lgkmcnt(14)
	v_mfma_f32_16x16x32_bf16 v[46:49], v[30:33], v[34:37], 0
	v_lshl_add_u64 v[62:63], s[50:51], 0, v[2:3]
	v_add_co_u32_e32 v160, vcc, s27, v62
	v_mfma_f32_16x16x32_bf16 v[30:33], v[30:33], v[50:53], 0
	s_nop 0
	v_addc_co_u32_e32 v161, vcc, 0, v63, vcc
	v_add_co_u32_e32 v162, vcc, s28, v62
	s_waitcnt lgkmcnt(13)
	v_mfma_f32_16x16x32_bf16 v[70:73], v[58:61], v[34:37], 0
	v_addc_co_u32_e32 v163, vcc, 0, v63, vcc
	v_add_co_u32_e32 v164, vcc, s29, v62
	v_mfma_f32_16x16x32_bf16 v[58:61], v[58:61], v[50:53], 0
	s_nop 0
	v_addc_co_u32_e32 v165, vcc, 0, v63, vcc
	v_add_co_u32_e32 v62, vcc, s30, v62
	s_waitcnt lgkmcnt(11)
	v_mfma_f32_16x16x32_bf16 v[82:85], v[74:77], v[34:37], 0
	v_addc_co_u32_e32 v63, vcc, 0, v63, vcc
	v_lshl_add_u64 v[2:3], v[2:3], 0, s[4:5]
	v_mfma_f32_16x16x32_bf16 v[74:77], v[74:77], v[50:53], 0
	s_waitcnt lgkmcnt(9)
	v_mfma_f32_16x16x32_bf16 v[94:97], v[86:89], v[34:37], 0
	v_mfma_f32_16x16x32_bf16 v[86:89], v[86:89], v[50:53], 0
	s_waitcnt lgkmcnt(7)
	v_mfma_f32_16x16x32_bf16 v[106:109], v[98:101], v[34:37], 0
	v_mfma_f32_16x16x32_bf16 v[98:101], v[98:101], v[50:53], 0
	s_waitcnt lgkmcnt(5)
	v_mfma_f32_16x16x32_bf16 v[118:121], v[110:113], v[34:37], 0
	s_waitcnt lgkmcnt(3)
	v_mfma_f32_16x16x32_bf16 v[134:137], v[122:125], v[34:37], 0
	s_waitcnt lgkmcnt(1)
	v_mfma_f32_16x16x32_bf16 v[34:37], v[138:141], v[34:37], 0
	v_mfma_f32_16x16x32_bf16 v[46:49], v[42:45], v[38:41], v[46:49]
	v_mfma_f32_16x16x32_bf16 v[30:33], v[42:45], v[54:57], v[30:33]
	v_mfma_f32_16x16x32_bf16 v[42:45], v[66:69], v[38:41], v[70:73]
	v_mfma_f32_16x16x32_bf16 v[58:61], v[66:69], v[54:57], v[58:61]
	v_mfma_f32_16x16x32_bf16 v[66:69], v[78:81], v[38:41], v[82:85]
	v_mfma_f32_16x16x32_bf16 v[70:73], v[78:81], v[54:57], v[74:77]
	v_mfma_f32_16x16x32_bf16 v[74:77], v[90:93], v[38:41], v[94:97]
	v_mfma_f32_16x16x32_bf16 v[78:81], v[90:93], v[54:57], v[86:89]
	v_mfma_f32_16x16x32_bf16 v[82:85], v[102:105], v[38:41], v[106:109]
	v_mfma_f32_16x16x32_bf16 v[86:89], v[102:105], v[54:57], v[98:101]
	v_mfma_f32_16x16x32_bf16 v[90:93], v[114:117], v[38:41], v[118:121]
	v_mfma_f32_16x16x32_bf16 v[98:101], v[130:133], v[38:41], v[134:137]
	s_waitcnt lgkmcnt(0)
	v_mfma_f32_16x16x32_bf16 v[34:37], v[142:145], v[38:41], v[34:37]
	ds_read_b128 v[38:41], v26 offset:128
	v_mfma_f32_16x16x32_bf16 v[110:113], v[110:113], v[50:53], 0
	v_mfma_f32_16x16x32_bf16 v[122:125], v[122:125], v[50:53], 0
	v_mfma_f32_16x16x32_bf16 v[50:53], v[138:141], v[50:53], 0
	v_mfma_f32_16x16x32_bf16 v[94:97], v[114:117], v[54:57], v[110:113]
	v_mfma_f32_16x16x32_bf16 v[102:105], v[130:133], v[54:57], v[122:125]
	v_mfma_f32_16x16x32_bf16 v[50:53], v[142:145], v[54:57], v[50:53]
	ds_read_b128 v[54:57], v17 offset:34944
	ds_read_b128 v[106:109], v17 offset:35008
	s_nop 0
	ds_read_b128 v[110:113], v26 offset:192
	ds_read_b128 v[114:117], v17 offset:39296
	ds_read_b128 v[118:121], v17 offset:39360
	s_waitcnt lgkmcnt(4)
	v_mfma_f32_16x16x32_bf16 v[46:49], v[38:41], v[54:57], v[46:49]
	s_waitcnt lgkmcnt(1)
	v_mfma_f32_16x16x32_bf16 v[30:33], v[38:41], v[114:117], v[30:33]
	ds_read_b128 v[38:41], v26 offset:4480
	ds_read_b128 v[122:125], v26 offset:4544
	s_waitcnt lgkmcnt(1)
	v_mfma_f32_16x16x32_bf16 v[42:45], v[38:41], v[54:57], v[42:45]
	v_mfma_f32_16x16x32_bf16 v[38:41], v[38:41], v[114:117], v[58:61]
	s_nop 2
	ds_read_b128 v[58:61], v26 offset:8832
	ds_read_b128 v[130:133], v26 offset:8896
	s_waitcnt lgkmcnt(1)
	v_mfma_f32_16x16x32_bf16 v[66:69], v[58:61], v[54:57], v[66:69]
	v_mfma_f32_16x16x32_bf16 v[58:61], v[58:61], v[114:117], v[70:73]
	s_nop 2
	ds_read_b128 v[70:73], v26 offset:13184
	ds_read_b128 v[134:137], v26 offset:13248
	s_waitcnt lgkmcnt(1)
	v_mfma_f32_16x16x32_bf16 v[74:77], v[70:73], v[54:57], v[74:77]
	v_mfma_f32_16x16x32_bf16 v[70:73], v[70:73], v[114:117], v[78:81]
	s_nop 2
	ds_read_b128 v[78:81], v26 offset:17536
	ds_read_b128 v[138:141], v26 offset:17600
	s_waitcnt lgkmcnt(1)
	v_mfma_f32_16x16x32_bf16 v[82:85], v[78:81], v[54:57], v[82:85]
	v_mfma_f32_16x16x32_bf16 v[78:81], v[78:81], v[114:117], v[86:89]
	s_nop 2
	ds_read_b128 v[86:89], v26 offset:21888
	ds_read_b128 v[142:145], v26 offset:21952
	s_waitcnt lgkmcnt(1)
	v_mfma_f32_16x16x32_bf16 v[90:93], v[86:89], v[54:57], v[90:93]
	v_mfma_f32_16x16x32_bf16 v[86:89], v[86:89], v[114:117], v[94:97]
	s_nop 2
	ds_read_b128 v[94:97], v26 offset:26240
	ds_read_b128 v[146:149], v26 offset:26304
	s_waitcnt lgkmcnt(1)
	v_mfma_f32_16x16x32_bf16 v[98:101], v[94:97], v[54:57], v[98:101]
	v_mfma_f32_16x16x32_bf16 v[94:97], v[94:97], v[114:117], v[102:105]
	s_nop 2
	ds_read_b128 v[102:105], v26 offset:30592
	ds_read_b128 v[150:153], v26 offset:30656
	s_waitcnt lgkmcnt(1)
	v_mfma_f32_16x16x32_bf16 v[34:37], v[102:105], v[54:57], v[34:37]
	v_mfma_f32_16x16x32_bf16 v[50:53], v[102:105], v[114:117], v[50:53]
	v_lshl_add_u64 v[102:103], s[50:51], 0, v[12:13]
	v_add_co_u32_e32 v166, vcc, s31, v102
	v_mfma_f32_16x16x32_bf16 v[46:49], v[110:113], v[106:109], v[46:49]
	s_nop 0
	v_addc_co_u32_e32 v167, vcc, 0, v103, vcc
	v_add_co_u32_e32 v168, vcc, s33, v102
	v_mfma_f32_16x16x32_bf16 v[30:33], v[110:113], v[118:121], v[30:33]
	s_nop 0
	v_addc_co_u32_e32 v169, vcc, 0, v103, vcc
	v_lshl_add_u64 v[12:13], v[12:13], 0, s[6:7]
	v_mfma_f32_16x16x32_bf16 v[42:45], v[122:125], v[106:109], v[42:45]
	v_mfma_f32_16x16x32_bf16 v[38:41], v[122:125], v[118:121], v[38:41]
	v_mfma_f32_16x16x32_bf16 v[54:57], v[130:133], v[106:109], v[66:69]
	v_mfma_f32_16x16x32_bf16 v[58:61], v[130:133], v[118:121], v[58:61]
	v_mfma_f32_16x16x32_bf16 v[66:69], v[134:137], v[106:109], v[74:77]
	v_mfma_f32_16x16x32_bf16 v[70:73], v[134:137], v[118:121], v[70:73]
	v_mfma_f32_16x16x32_bf16 v[74:77], v[138:141], v[106:109], v[82:85]
	s_nop 2
	ds_read_b128 v[82:85], v20 offset:34816
	ds_read_b128 v[102:105], v20 offset:52224
	ds_read_b128 v[110:113], v21 offset:34816
	ds_read_b128 v[114:117], v22 offset:34816
	ds_read_b128 v[122:125], v24 offset:34816
	ds_read_b128 v[130:133], v23 offset:34816
	ds_read_b128 v[134:137], v23 offset:52224
	v_mfma_f32_16x16x32_bf16 v[78:81], v[138:141], v[118:121], v[78:81]
	ds_read_b128 v[138:141], v25 offset:34816
	s_waitcnt lgkmcnt(7)
	global_store_dwordx4 v[160:161], v[82:85], off
	s_waitcnt lgkmcnt(5)
	global_store_dwordx4 v[126:127], v[110:113], off
	global_store_dwordx4 v[162:163], v[102:105], off
	s_waitcnt lgkmcnt(4)
	global_store_dwordx4 v[154:155], v[114:117], off
	s_waitcnt lgkmcnt(2)
	global_store_dwordx4 v[164:165], v[130:133], off
	v_mfma_f32_16x16x32_bf16 v[90:93], v[142:145], v[106:109], v[90:93]
	global_store_dwordx4 v[156:157], v[122:125], off
	s_waitcnt lgkmcnt(1)
	global_store_dwordx4 v[62:63], v[134:137], off
	s_waitcnt lgkmcnt(0)
	global_store_dwordx4 v[158:159], v[138:141], off
	v_mfma_f32_16x16x32_bf16 v[86:89], v[142:145], v[118:121], v[86:89]
	v_mfma_f32_16x16x32_bf16 v[98:101], v[146:149], v[106:109], v[98:101]
	v_mfma_f32_16x16x32_bf16 v[82:85], v[146:149], v[118:121], v[94:97]
	v_mfma_f32_16x16x32_bf16 v[34:37], v[150:153], v[106:109], v[34:37]
	v_mfma_f32_16x16x32_bf16 v[50:53], v[150:153], v[118:121], v[50:53]
	global_store_dwordx4 v[166:167], v[46:49], off
	v_and_b32_e32 v254, 63, v128
	v_and_b32_e32 v255, 3, v254
	v_lshrrev_b32_e32 v254, 2, v254
	v_lshl_or_b32 v254, v255, 4, v254
	v_lshlrev_b32_e32 v254, 2, v254
	ds_bpermute_b32 v238, v254, v42
	ds_bpermute_b32 v239, v254, v43
	ds_bpermute_b32 v240, v254, v44
	ds_bpermute_b32 v241, v254, v45
	ds_bpermute_b32 v236, v254, v166
	ds_bpermute_b32 v237, v254, v167
	ds_bpermute_b32 v244, v254, v54
	ds_bpermute_b32 v245, v254, v55
	ds_bpermute_b32 v246, v254, v56
	ds_bpermute_b32 v247, v254, v57
	ds_bpermute_b32 v242, v254, v166
	ds_bpermute_b32 v243, v254, v167
	ds_bpermute_b32 v250, v254, v66
	ds_bpermute_b32 v251, v254, v67
	ds_bpermute_b32 v252, v254, v68
	ds_bpermute_b32 v253, v254, v69
	ds_bpermute_b32 v248, v254, v166
	ds_bpermute_b32 v249, v254, v167
	s_waitcnt lgkmcnt(12)
	global_store_dwordx4 v[236:237], v[238:241], off offset:64
	s_nop 0
	ds_bpermute_b32 v238, v254, v74
	ds_bpermute_b32 v239, v254, v75
	ds_bpermute_b32 v240, v254, v76
	ds_bpermute_b32 v241, v254, v77
	ds_bpermute_b32 v236, v254, v166
	ds_bpermute_b32 v237, v254, v167
	s_waitcnt lgkmcnt(12)
	global_store_dwordx4 v[242:243], v[244:247], off offset:128
	s_nop 0
	ds_bpermute_b32 v244, v254, v90
	ds_bpermute_b32 v245, v254, v91
	ds_bpermute_b32 v246, v254, v92
	ds_bpermute_b32 v247, v254, v93
	ds_bpermute_b32 v242, v254, v166
	ds_bpermute_b32 v243, v254, v167
	s_waitcnt lgkmcnt(12)
	global_store_dwordx4 v[248:249], v[250:253], off offset:192
	s_nop 0
	ds_bpermute_b32 v250, v254, v98
	ds_bpermute_b32 v251, v254, v99
	ds_bpermute_b32 v252, v254, v100
	ds_bpermute_b32 v253, v254, v101
	ds_bpermute_b32 v248, v254, v166
	ds_bpermute_b32 v249, v254, v167
	s_waitcnt lgkmcnt(12)
	global_store_dwordx4 v[236:237], v[238:241], off offset:256
	s_nop 0
	ds_bpermute_b32 v238, v254, v34
	ds_bpermute_b32 v239, v254, v35
	ds_bpermute_b32 v240, v254, v36
	ds_bpermute_b32 v241, v254, v37
	ds_bpermute_b32 v236, v254, v166
	ds_bpermute_b32 v237, v254, v167
	s_waitcnt lgkmcnt(12)
	global_store_dwordx4 v[242:243], v[244:247], off offset:320
	s_nop 0
	ds_bpermute_b32 v244, v254, v30
	ds_bpermute_b32 v245, v254, v31
	ds_bpermute_b32 v246, v254, v32
	ds_bpermute_b32 v247, v254, v33
	ds_bpermute_b32 v242, v254, v168
	ds_bpermute_b32 v243, v254, v169
	s_waitcnt lgkmcnt(12)
	global_store_dwordx4 v[248:249], v[250:253], off offset:384
	s_nop 0
	ds_bpermute_b32 v250, v254, v38
	ds_bpermute_b32 v251, v254, v39
	ds_bpermute_b32 v252, v254, v40
	ds_bpermute_b32 v253, v254, v41
	ds_bpermute_b32 v248, v254, v168
	ds_bpermute_b32 v249, v254, v169
	s_waitcnt lgkmcnt(12)
	global_store_dwordx4 v[236:237], v[238:241], off offset:448
	s_nop 0
	ds_bpermute_b32 v238, v254, v58
	ds_bpermute_b32 v239, v254, v59
	ds_bpermute_b32 v240, v254, v60
	ds_bpermute_b32 v241, v254, v61
	ds_bpermute_b32 v236, v254, v168
	ds_bpermute_b32 v237, v254, v169
	s_waitcnt lgkmcnt(12)
	global_store_dwordx4 v[242:243], v[244:247], off
	s_nop 0
	ds_bpermute_b32 v244, v254, v70
	ds_bpermute_b32 v245, v254, v71
	ds_bpermute_b32 v246, v254, v72
	ds_bpermute_b32 v247, v254, v73
	ds_bpermute_b32 v242, v254, v168
	ds_bpermute_b32 v243, v254, v169
	s_waitcnt lgkmcnt(12)
	global_store_dwordx4 v[248:249], v[250:253], off offset:64
	s_nop 0
	ds_bpermute_b32 v250, v254, v78
	ds_bpermute_b32 v251, v254, v79
	ds_bpermute_b32 v252, v254, v80
	ds_bpermute_b32 v253, v254, v81
	ds_bpermute_b32 v248, v254, v168
	ds_bpermute_b32 v249, v254, v169
	s_waitcnt lgkmcnt(12)
	global_store_dwordx4 v[236:237], v[238:241], off offset:128
	s_nop 0
	ds_bpermute_b32 v238, v254, v86
	ds_bpermute_b32 v239, v254, v87
	ds_bpermute_b32 v240, v254, v88
	ds_bpermute_b32 v241, v254, v89
	ds_bpermute_b32 v236, v254, v168
	ds_bpermute_b32 v237, v254, v169
	s_waitcnt lgkmcnt(12)
	global_store_dwordx4 v[242:243], v[244:247], off offset:192
	s_nop 0
	ds_bpermute_b32 v244, v254, v82
	ds_bpermute_b32 v245, v254, v83
	ds_bpermute_b32 v246, v254, v84
	ds_bpermute_b32 v247, v254, v85
	ds_bpermute_b32 v242, v254, v168
	ds_bpermute_b32 v243, v254, v169
	s_waitcnt lgkmcnt(12)
	global_store_dwordx4 v[248:249], v[250:253], off offset:256
	s_nop 0
	ds_bpermute_b32 v250, v254, v50
	ds_bpermute_b32 v251, v254, v51
	ds_bpermute_b32 v252, v254, v52
	ds_bpermute_b32 v253, v254, v53
	ds_bpermute_b32 v248, v254, v168
	ds_bpermute_b32 v249, v254, v169
	s_waitcnt lgkmcnt(12)
	global_store_dwordx4 v[236:237], v[238:241], off offset:320
	s_waitcnt lgkmcnt(6)
	global_store_dwordx4 v[242:243], v[244:247], off offset:384
	s_waitcnt lgkmcnt(0)
	global_store_dwordx4 v[248:249], v[250:253], off offset:448
	s_barrier
	s_cbranch_scc0 .LBB0_973

.LBB0_1393:
	v_lshl_or_b32 v146, s30, 8, v157
	v_lshl_add_u32 v148, s52, 8, v129
	v_ashrrev_i32_e32 v147, 31, v146
	v_mov_b64_e32 v[150:151], s[8:9]
	v_mad_i64_i32 v[154:155], s[54:55], v148, s71, v[150:151]
	v_lshlrev_b64 v[152:153], 1, v[146:147]
	v_lshl_add_u64 v[154:155], v[154:155], 0, v[152:153]
	v_add_co_u32_e32 v162, vcc, 0x3000, v154
	v_or_b32_e32 v182, 16, v148
	s_nop 0
	v_addc_co_u32_e32 v163, vcc, 0, v155, vcc
	v_lshl_add_u64 v[154:155], v[154:155], 0, s[18:19]
	global_load_dwordx4 v[162:165], v[162:163], off offset:3072 nt
	v_or_b32_e32 v194, 32, v148
	global_load_dwordx4 v[166:169], v[154:155], off offset:256 nt
	v_mad_i64_i32 v[154:155], s[54:55], v182, s71, v[150:151]
	v_lshl_add_u64 v[154:155], v[154:155], 0, v[152:153]
	v_add_co_u32_e32 v170, vcc, s72, v154
	v_mad_i64_i32 v[178:179], s[54:55], v194, s71, v[150:151]
	s_nop 0
	v_addc_co_u32_e32 v171, vcc, 0, v155, vcc
	global_load_dwordx4 v[170:173], v[170:171], off offset:3072 nt
	v_lshl_add_u64 v[154:155], v[154:155], 0, s[18:19]
	global_load_dwordx4 v[174:177], v[154:155], off offset:256 nt
	v_lshl_add_u64 v[184:185], v[178:179], 0, v[152:153]
	v_add_co_u32_e32 v178, vcc, s72, v184
	v_ashrrev_i32_e32 v183, 31, v182
	s_nop 0
	v_addc_co_u32_e32 v179, vcc, 0, v185, vcc
	global_load_dwordx4 v[178:181], v[178:179], off offset:3072 nt
	v_lshlrev_b64 v[196:197], 13, v[182:183]
	v_lshl_add_u64 v[182:183], v[184:185], 0, s[18:19]
	v_or_b32_e32 v154, 48, v148
	global_load_dwordx4 v[182:185], v[182:183], off offset:256 nt
	v_mad_i64_i32 v[186:187], s[54:55], v154, s71, v[150:151]
	v_ashrrev_i32_e32 v149, 31, v148
	v_lshl_add_u64 v[186:187], v[186:187], 0, v[152:153]
	v_lshlrev_b64 v[188:189], 13, v[148:149]
	v_lshl_add_u64 v[190:191], v[186:187], 0, s[18:19]
	v_add_co_u32_e32 v186, vcc, s72, v186
	v_lshlrev_b64 v[146:147], 2, v[146:147]
	v_lshl_add_u64 v[188:189], s[6:7], 0, v[188:189]
	v_addc_co_u32_e32 v187, vcc, 0, v187, vcc
	v_lshl_add_u64 v[198:199], v[188:189], 0, v[146:147]
	global_load_dwordx4 v[186:189], v[186:187], off offset:3072 nt
	s_nop 0
	global_load_dwordx4 v[190:193], v[190:191], off offset:256 nt
	v_ashrrev_i32_e32 v195, 31, v194
	v_ashrrev_i32_e32 v155, 31, v154
	s_waitcnt vmcnt(0)
	v_lshlrev_b32_e32 v200, 16, v162
	v_and_b32_e32 v201, 0xffff0000, v162
	v_lshlrev_b32_e32 v162, 16, v163
	v_and_b32_e32 v163, 0xffff0000, v163
	v_lshlrev_b32_e32 v204, 16, v166
	v_and_b32_e32 v205, 0xffff0000, v166
	v_lshlrev_b32_e32 v202, 16, v164
	v_and_b32_e32 v203, 0xffff0000, v164
	v_lshlrev_b32_e32 v164, 16, v165
	v_and_b32_e32 v165, 0xffff0000, v165
	v_lshlrev_b32_e32 v166, 16, v167
	v_and_b32_e32 v167, 0xffff0000, v167
	v_lshlrev_b32_e32 v206, 16, v168
	v_and_b32_e32 v207, 0xffff0000, v168
	v_lshlrev_b32_e32 v168, 16, v169
	v_and_b32_e32 v169, 0xffff0000, v169
	v_pk_mul_f32 v[124:125], v[124:125], v[200:201]
	v_pk_mul_f32 v[126:127], v[126:127], v[162:163]
	v_pk_mul_f32 v[112:113], v[112:113], v[204:205]
	v_pk_mul_f32 v[120:121], v[120:121], v[202:203]
	v_pk_mul_f32 v[122:123], v[122:123], v[164:165]
	v_pk_mul_f32 v[114:115], v[114:115], v[166:167]
	v_pk_mul_f32 v[108:109], v[108:109], v[206:207]
	v_pk_mul_f32 v[110:111], v[110:111], v[168:169]
	global_store_dwordx4 v[198:199], v[124:127], off
	global_store_dwordx4 v[198:199], v[120:123], off offset:16
	global_store_dwordx4 v[198:199], v[112:115], off offset:512
	global_store_dwordx4 v[198:199], v[108:111], off offset:528
	s_nop 0
	v_lshlrev_b32_e32 v112, 16, v172
	v_and_b32_e32 v113, 0xffff0000, v172
	v_pk_mul_f32 v[104:105], v[104:105], v[112:113]
	v_lshlrev_b32_e32 v112, 16, v173
	v_and_b32_e32 v113, 0xffff0000, v173
	v_lshlrev_b32_e32 v108, 16, v170
	v_and_b32_e32 v109, 0xffff0000, v170
	v_lshlrev_b32_e32 v110, 16, v171
	v_and_b32_e32 v111, 0xffff0000, v171
	v_pk_mul_f32 v[106:107], v[106:107], v[112:113]
	v_lshl_add_u64 v[112:113], s[6:7], 0, v[196:197]
	v_pk_mul_f32 v[108:109], v[116:117], v[108:109]
	v_pk_mul_f32 v[110:111], v[118:119], v[110:111]
	v_lshl_add_u64 v[112:113], v[112:113], 0, v[146:147]
	global_store_dwordx4 v[112:113], v[108:111], off
	global_store_dwordx4 v[112:113], v[104:107], off offset:16
	s_nop 1
	v_lshlrev_b32_e32 v104, 16, v174
	v_and_b32_e32 v105, 0xffff0000, v174
	v_pk_mul_f32 v[100:101], v[100:101], v[104:105]
	v_lshlrev_b32_e32 v104, 16, v175
	v_and_b32_e32 v105, 0xffff0000, v175
	v_pk_mul_f32 v[102:103], v[102:103], v[104:105]
	v_lshlrev_b32_e32 v104, 16, v176
	v_and_b32_e32 v105, 0xffff0000, v176
	v_pk_mul_f32 v[92:93], v[92:93], v[104:105]
	v_lshlrev_b32_e32 v104, 16, v177
	v_and_b32_e32 v105, 0xffff0000, v177
	v_pk_mul_f32 v[94:95], v[94:95], v[104:105]
	global_store_dwordx4 v[112:113], v[100:103], off offset:512
	global_store_dwordx4 v[112:113], v[92:95], off offset:528
	s_nop 0
	v_lshlrev_b64 v[100:101], 13, v[194:195]
	v_lshlrev_b32_e32 v92, 16, v178
	v_and_b32_e32 v93, 0xffff0000, v178
	v_pk_mul_f32 v[92:93], v[96:97], v[92:93]
	v_lshlrev_b32_e32 v96, 16, v180
	v_and_b32_e32 v97, 0xffff0000, v180
	v_pk_mul_f32 v[88:89], v[88:89], v[96:97]
	v_lshlrev_b32_e32 v96, 16, v181
	v_and_b32_e32 v97, 0xffff0000, v181
	v_lshlrev_b32_e32 v94, 16, v179
	v_and_b32_e32 v95, 0xffff0000, v179
	v_pk_mul_f32 v[90:91], v[90:91], v[96:97]
	v_lshl_add_u64 v[96:97], s[6:7], 0, v[100:101]
	v_pk_mul_f32 v[94:95], v[98:99], v[94:95]
	v_lshl_add_u64 v[96:97], v[96:97], 0, v[146:147]
	global_store_dwordx4 v[96:97], v[92:95], off
	global_store_dwordx4 v[96:97], v[88:91], off offset:16
	v_add_u32_e32 v98, 0x90, v148
	v_add_u32_e32 v100, 0xa0, v148
	v_lshlrev_b32_e32 v88, 16, v182
	v_and_b32_e32 v89, 0xffff0000, v182
	v_pk_mul_f32 v[84:85], v[84:85], v[88:89]
	v_lshlrev_b32_e32 v88, 16, v183
	v_and_b32_e32 v89, 0xffff0000, v183
	v_pk_mul_f32 v[86:87], v[86:87], v[88:89]
	v_lshlrev_b32_e32 v88, 16, v184
	v_and_b32_e32 v89, 0xffff0000, v184
	v_pk_mul_f32 v[76:77], v[76:77], v[88:89]
	v_lshlrev_b32_e32 v88, 16, v185
	v_and_b32_e32 v89, 0xffff0000, v185
	v_pk_mul_f32 v[78:79], v[78:79], v[88:89]
	global_store_dwordx4 v[96:97], v[84:87], off offset:512
	global_store_dwordx4 v[96:97], v[76:79], off offset:528
	v_add_u32_e32 v96, 0x80, v148
	v_lshlrev_b64 v[84:85], 13, v[154:155]
	v_lshlrev_b32_e32 v76, 16, v186
	v_and_b32_e32 v77, 0xffff0000, v186
	v_pk_mul_f32 v[76:77], v[80:81], v[76:77]
	v_lshlrev_b32_e32 v80, 16, v188
	v_and_b32_e32 v81, 0xffff0000, v188
	v_pk_mul_f32 v[72:73], v[72:73], v[80:81]
	v_lshlrev_b32_e32 v80, 16, v189
	v_and_b32_e32 v81, 0xffff0000, v189
	v_lshlrev_b32_e32 v78, 16, v187
	v_and_b32_e32 v79, 0xffff0000, v187
	v_pk_mul_f32 v[74:75], v[74:75], v[80:81]
	v_lshl_add_u64 v[80:81], s[6:7], 0, v[84:85]
	v_pk_mul_f32 v[78:79], v[82:83], v[78:79]
	v_lshl_add_u64 v[80:81], v[80:81], 0, v[146:147]
	global_store_dwordx4 v[80:81], v[76:79], off
	global_store_dwordx4 v[80:81], v[72:75], off offset:16
	v_add_u32_e32 v102, 0xb0, v148
	v_ashrrev_i32_e32 v97, 31, v96
	v_lshlrev_b32_e32 v72, 16, v190
	v_and_b32_e32 v73, 0xffff0000, v190
	v_pk_mul_f32 v[68:69], v[68:69], v[72:73]
	v_lshlrev_b32_e32 v72, 16, v191
	v_and_b32_e32 v73, 0xffff0000, v191
	v_pk_mul_f32 v[70:71], v[70:71], v[72:73]
	v_lshlrev_b32_e32 v72, 16, v192
	v_and_b32_e32 v73, 0xffff0000, v192
	v_pk_mul_f32 v[64:65], v[64:65], v[72:73]
	v_lshlrev_b32_e32 v72, 16, v193
	v_and_b32_e32 v73, 0xffff0000, v193
	v_pk_mul_f32 v[66:67], v[66:67], v[72:73]
	global_store_dwordx4 v[80:81], v[68:71], off offset:512
	global_store_dwordx4 v[80:81], v[64:67], off offset:528
	v_ashrrev_i32_e32 v99, 31, v98
	v_ashrrev_i32_e32 v101, 31, v100
	v_mad_i64_i32 v[64:65], s[54:55], v96, s71, v[150:151]
	v_lshl_add_u64 v[64:65], v[64:65], 0, v[152:153]
	v_add_co_u32_e32 v66, vcc, s72, v64
	v_lshlrev_b64 v[96:97], 13, v[96:97]
	s_nop 0
	v_addc_co_u32_e32 v67, vcc, 0, v65, vcc
	global_load_dwordx4 v[68:71], v[66:67], off offset:3072 nt
	v_lshl_add_u64 v[64:65], v[64:65], 0, s[18:19]
	global_load_dwordx4 v[72:75], v[64:65], off offset:256 nt
	v_mad_i64_i32 v[64:65], s[54:55], v98, s71, v[150:151]
	v_lshl_add_u64 v[64:65], v[64:65], 0, v[152:153]
	v_add_co_u32_e32 v66, vcc, s72, v64
	v_ashrrev_i32_e32 v103, 31, v102
	s_nop 0
	v_addc_co_u32_e32 v67, vcc, 0, v65, vcc
	global_load_dwordx4 v[76:79], v[66:67], off offset:3072 nt
	v_lshl_add_u64 v[64:65], v[64:65], 0, s[18:19]
	global_load_dwordx4 v[80:83], v[64:65], off offset:256 nt
	v_mad_i64_i32 v[64:65], s[54:55], v100, s71, v[150:151]
	v_lshl_add_u64 v[64:65], v[64:65], 0, v[152:153]
	v_add_co_u32_e32 v66, vcc, s72, v64
	s_waitcnt vmcnt(3)
	v_lshlrev_b32_e32 v104, 16, v68
	v_addc_co_u32_e32 v67, vcc, 0, v65, vcc
	global_load_dwordx4 v[84:87], v[66:67], off offset:3072 nt
	v_lshl_add_u64 v[64:65], v[64:65], 0, s[18:19]
	global_load_dwordx4 v[88:91], v[64:65], off offset:256 nt
	v_mad_i64_i32 v[64:65], s[54:55], v102, s71, v[150:151]
	v_lshl_add_u64 v[64:65], v[64:65], 0, v[152:153]
	v_lshl_add_u64 v[66:67], v[64:65], 0, s[18:19]
	v_add_co_u32_e32 v64, vcc, s72, v64
	v_and_b32_e32 v105, 0xffff0000, v68
	s_nop 0
	v_addc_co_u32_e32 v65, vcc, 0, v65, vcc
	global_load_dwordx4 v[92:95], v[64:65], off offset:3072 nt
	s_nop 0
	global_load_dwordx4 v[64:67], v[66:67], off offset:256 nt
	v_lshlrev_b32_e32 v68, 16, v69
	v_and_b32_e32 v69, 0xffff0000, v69
	v_pk_mul_f32 v[62:63], v[62:63], v[68:69]
	v_lshlrev_b32_e32 v68, 16, v70
	v_and_b32_e32 v69, 0xffff0000, v70
	v_pk_mul_f32 v[56:57], v[56:57], v[68:69]
	v_lshlrev_b32_e32 v68, 16, v71
	v_and_b32_e32 v69, 0xffff0000, v71
	v_pk_mul_f32 v[58:59], v[58:59], v[68:69]
	v_lshl_add_u64 v[68:69], s[6:7], 0, v[96:97]
	v_pk_mul_f32 v[60:61], v[60:61], v[104:105]
	v_lshl_add_u64 v[68:69], v[68:69], 0, v[146:147]
	global_store_dwordx4 v[68:69], v[60:63], off
	global_store_dwordx4 v[68:69], v[56:59], off offset:16
	s_andn2_b64 vcc, exec, s[4:5]
	s_mov_b64 s[4:5], -1
	s_waitcnt vmcnt(8)
	v_lshlrev_b32_e32 v56, 16, v72
	v_and_b32_e32 v57, 0xffff0000, v72
	v_pk_mul_f32 v[52:53], v[52:53], v[56:57]
	v_lshlrev_b32_e32 v56, 16, v73
	v_and_b32_e32 v57, 0xffff0000, v73
	v_pk_mul_f32 v[54:55], v[54:55], v[56:57]
	v_lshlrev_b32_e32 v56, 16, v74
	v_and_b32_e32 v57, 0xffff0000, v74
	v_pk_mul_f32 v[44:45], v[44:45], v[56:57]
	v_lshlrev_b32_e32 v56, 16, v75
	v_and_b32_e32 v57, 0xffff0000, v75
	v_pk_mul_f32 v[46:47], v[46:47], v[56:57]
	global_store_dwordx4 v[68:69], v[52:55], off offset:512
	global_store_dwordx4 v[68:69], v[44:47], off offset:528
	s_nop 0
	v_lshlrev_b64 v[52:53], 13, v[98:99]
	s_waitcnt vmcnt(9)
	v_lshlrev_b32_e32 v44, 16, v76
	v_and_b32_e32 v45, 0xffff0000, v76
	v_pk_mul_f32 v[44:45], v[48:49], v[44:45]
	v_lshlrev_b32_e32 v48, 16, v78
	v_and_b32_e32 v49, 0xffff0000, v78
	v_pk_mul_f32 v[40:41], v[40:41], v[48:49]
	v_lshlrev_b32_e32 v48, 16, v79
	v_and_b32_e32 v49, 0xffff0000, v79
	v_lshlrev_b32_e32 v46, 16, v77
	v_and_b32_e32 v47, 0xffff0000, v77
	v_pk_mul_f32 v[42:43], v[42:43], v[48:49]
	v_lshl_add_u64 v[48:49], s[6:7], 0, v[52:53]
	v_pk_mul_f32 v[46:47], v[50:51], v[46:47]
	v_lshl_add_u64 v[48:49], v[48:49], 0, v[146:147]
	global_store_dwordx4 v[48:49], v[44:47], off
	global_store_dwordx4 v[48:49], v[40:43], off offset:16
	s_waitcnt vmcnt(10)
	s_nop 0
	v_lshlrev_b32_e32 v40, 16, v80
	v_and_b32_e32 v41, 0xffff0000, v80
	v_pk_mul_f32 v[36:37], v[36:37], v[40:41]
	v_lshlrev_b32_e32 v40, 16, v81
	v_and_b32_e32 v41, 0xffff0000, v81
	v_pk_mul_f32 v[38:39], v[38:39], v[40:41]
	v_lshlrev_b32_e32 v40, 16, v82
	v_and_b32_e32 v41, 0xffff0000, v82
	v_pk_mul_f32 v[28:29], v[28:29], v[40:41]
	v_lshlrev_b32_e32 v40, 16, v83
	v_and_b32_e32 v41, 0xffff0000, v83
	v_pk_mul_f32 v[30:31], v[30:31], v[40:41]
	global_store_dwordx4 v[48:49], v[36:39], off offset:512
	global_store_dwordx4 v[48:49], v[28:31], off offset:528
	s_nop 0
	v_lshlrev_b64 v[36:37], 13, v[100:101]
	s_waitcnt vmcnt(11)
	v_lshlrev_b32_e32 v28, 16, v84
	v_and_b32_e32 v29, 0xffff0000, v84
	v_pk_mul_f32 v[28:29], v[32:33], v[28:29]
	v_lshlrev_b32_e32 v32, 16, v86
	v_and_b32_e32 v33, 0xffff0000, v86
	v_pk_mul_f32 v[24:25], v[24:25], v[32:33]
	v_lshlrev_b32_e32 v32, 16, v87
	v_and_b32_e32 v33, 0xffff0000, v87
	v_lshlrev_b32_e32 v30, 16, v85
	v_and_b32_e32 v31, 0xffff0000, v85
	v_pk_mul_f32 v[26:27], v[26:27], v[32:33]
	v_lshl_add_u64 v[32:33], s[6:7], 0, v[36:37]
	v_pk_mul_f32 v[30:31], v[34:35], v[30:31]
	v_lshl_add_u64 v[32:33], v[32:33], 0, v[146:147]
	global_store_dwordx4 v[32:33], v[28:31], off
	global_store_dwordx4 v[32:33], v[24:27], off offset:16
	s_waitcnt vmcnt(12)
	s_nop 0
	v_lshlrev_b32_e32 v24, 16, v88
	v_and_b32_e32 v25, 0xffff0000, v88
	v_pk_mul_f32 v[20:21], v[20:21], v[24:25]
	v_lshlrev_b32_e32 v24, 16, v89
	v_and_b32_e32 v25, 0xffff0000, v89
	v_pk_mul_f32 v[22:23], v[22:23], v[24:25]
	v_lshlrev_b32_e32 v24, 16, v90
	v_and_b32_e32 v25, 0xffff0000, v90
	v_pk_mul_f32 v[12:13], v[12:13], v[24:25]
	v_lshlrev_b32_e32 v24, 16, v91
	v_and_b32_e32 v25, 0xffff0000, v91
	v_pk_mul_f32 v[14:15], v[14:15], v[24:25]
	global_store_dwordx4 v[32:33], v[20:23], off offset:512
	global_store_dwordx4 v[32:33], v[12:15], off offset:528
	s_nop 0
	v_lshlrev_b64 v[20:21], 13, v[102:103]
	s_waitcnt vmcnt(13)
	v_lshlrev_b32_e32 v12, 16, v92
	v_and_b32_e32 v13, 0xffff0000, v92
	v_pk_mul_f32 v[12:13], v[16:17], v[12:13]
	v_lshlrev_b32_e32 v16, 16, v94
	v_and_b32_e32 v17, 0xffff0000, v94
	v_pk_mul_f32 v[8:9], v[8:9], v[16:17]
	v_lshlrev_b32_e32 v16, 16, v95
	v_and_b32_e32 v17, 0xffff0000, v95
	v_lshlrev_b32_e32 v14, 16, v93
	v_and_b32_e32 v15, 0xffff0000, v93
	v_pk_mul_f32 v[10:11], v[10:11], v[16:17]
	v_lshl_add_u64 v[16:17], s[6:7], 0, v[20:21]
	v_pk_mul_f32 v[14:15], v[18:19], v[14:15]
	v_lshl_add_u64 v[16:17], v[16:17], 0, v[146:147]
	global_store_dwordx4 v[16:17], v[12:15], off
	global_store_dwordx4 v[16:17], v[8:11], off offset:16
	s_waitcnt vmcnt(14)
	s_nop 0
	v_lshlrev_b32_e32 v8, 16, v64
	v_and_b32_e32 v9, 0xffff0000, v64
	v_pk_mul_f32 v[4:5], v[4:5], v[8:9]
	v_lshlrev_b32_e32 v8, 16, v65
	v_and_b32_e32 v9, 0xffff0000, v65
	v_pk_mul_f32 v[6:7], v[6:7], v[8:9]
	v_lshlrev_b32_e32 v8, 16, v66
	v_and_b32_e32 v9, 0xffff0000, v66
	v_pk_mul_f32 v[0:1], v[0:1], v[8:9]
	v_lshlrev_b32_e32 v8, 16, v67
	v_and_b32_e32 v9, 0xffff0000, v67
	v_pk_mul_f32 v[2:3], v[2:3], v[8:9]
	global_store_dwordx4 v[16:17], v[4:7], off offset:512
	global_store_dwordx4 v[16:17], v[0:3], off offset:528
	s_cmp_eq_u32 s87, 1
	s_cbranch_scc0 .Lp3_early_done
	s_cmp_lg_u32 s64, 1
	s_cbranch_scc1 .Lp3_early_done
	s_waitcnt vmcnt(0)
	s_barrier
	v_cmp_eq_u32_e64 s[84:85], 0, v128
	s_and_saveexec_b64 s[88:89], s[84:85]
	s_cbranch_execz .Lp3_early_x
	buffer_wbl2 sc1
	s_waitcnt vmcnt(0)
	s_lshl_b32 s86, s34, 2
	v_mov_b32_e32 v252, s86
	v_mov_b32_e32 v253, 1
	global_atomic_add v252, v253, s[50:51]

.Lpapr_nowait:
	v_lshl_add_u32 v148, s54, 8, v129
	v_lshl_or_b32 v152, s52, 8, v155
	v_ashrrev_i32_e32 v153, 31, v152
	v_mov_b64_e32 v[150:151], s[8:9]
	v_or_b32_e32 v208, 16, v148
	v_lshlrev_b64 v[146:147], 1, v[152:153]
	v_mad_i64_i32 v[164:165], s[56:57], v208, s74, v[150:151]
	v_lshl_add_u64 v[196:197], v[164:165], 0, v[146:147]
	v_mad_i64_i32 v[160:161], s[56:57], v148, s74, v[150:151]
	v_add_co_u32_e32 v164, vcc, s67, v196
	v_lshl_add_u64 v[168:169], v[160:161], 0, v[146:147]
	s_nop 0
	v_addc_co_u32_e32 v165, vcc, 0, v197, vcc
	v_ashrrev_i32_e32 v149, 31, v148
	v_lshl_add_u64 v[160:161], v[168:169], 0, s[20:21]
	v_add_co_u32_e32 v168, vcc, s67, v168
	v_lshl_add_u64 v[152:153], v[152:153], 2, s[6:7]
	v_lshlrev_b64 v[172:173], 13, v[148:149]
	v_ashrrev_i32_e32 v209, 31, v208
	global_load_dwordx4 v[160:163], v[160:161], off offset:256 nt
	v_addc_co_u32_e32 v169, vcc, 0, v169, vcc
	v_lshl_add_u64 v[192:193], v[152:153], 0, v[172:173]
	v_lshlrev_b64 v[180:181], 13, v[208:209]
	global_load_dwordx4 v[164:167], v[164:165], off offset:3072 nt
	v_lshl_add_u64 v[204:205], v[152:153], 0, v[180:181]
	global_load_dwordx4 v[168:171], v[168:169], off offset:3072 nt
	s_nop 0
	global_load_dwordx4 v[172:175], v[192:193], off offset:528
	global_load_dwordx4 v[176:179], v[192:193], off offset:512
	global_load_dwordx4 v[180:183], v[204:205], off
	global_load_dwordx4 v[184:187], v[204:205], off offset:16
	global_load_dwordx4 v[188:191], v[192:193], off
	s_nop 0
	global_load_dwordx4 v[192:195], v[192:193], off offset:16
	v_lshl_add_u64 v[196:197], v[196:197], 0, s[20:21]
	global_load_dwordx4 v[196:199], v[196:197], off offset:256 nt
	s_nop 0
	global_load_dwordx4 v[200:203], v[204:205], off offset:512
	s_nop 0
	global_load_dwordx4 v[204:207], v[204:205], off offset:528
	v_lshlrev_b64 v[210:211], 12, v[148:149]
	v_lshl_add_u64 v[210:211], s[14:15], 0, v[210:211]
	v_lshl_add_u64 v[210:211], v[210:211], 0, v[146:147]
	v_lshlrev_b64 v[208:209], 12, v[208:209]
	s_waitcnt vmcnt(0)
	v_lshlrev_b32_e32 v212, 16, v160
	v_and_b32_e32 v213, 0xffff0000, v160
	v_lshlrev_b32_e32 v160, 16, v161
	v_and_b32_e32 v161, 0xffff0000, v161
	v_lshlrev_b32_e32 v214, 16, v162
	v_and_b32_e32 v215, 0xffff0000, v162
	v_lshlrev_b32_e32 v162, 16, v163
	v_and_b32_e32 v163, 0xffff0000, v163
	v_lshlrev_b32_e32 v216, 16, v164
	v_and_b32_e32 v217, 0xffff0000, v164
	v_lshlrev_b32_e32 v164, 16, v165
	v_and_b32_e32 v165, 0xffff0000, v165
	v_lshlrev_b32_e32 v218, 16, v166
	v_and_b32_e32 v219, 0xffff0000, v166
	v_lshlrev_b32_e32 v220, 16, v168
	v_and_b32_e32 v221, 0xffff0000, v168
	v_lshlrev_b32_e32 v168, 16, v169
	v_and_b32_e32 v169, 0xffff0000, v169
	v_lshlrev_b32_e32 v222, 16, v170
	v_and_b32_e32 v223, 0xffff0000, v170
	v_lshlrev_b32_e32 v170, 16, v171
	v_and_b32_e32 v171, 0xffff0000, v171
	v_pk_fma_f32 v[112:113], v[112:113], v[212:213], v[176:177]
	v_pk_fma_f32 v[114:115], v[114:115], v[160:161], v[178:179]
	v_pk_fma_f32 v[160:161], v[108:109], v[214:215], v[172:173]
	v_pk_fma_f32 v[162:163], v[110:111], v[162:163], v[174:175]
	v_lshlrev_b32_e32 v166, 16, v167
	v_pk_fma_f32 v[122:123], v[122:123], v[164:165], v[182:183]
	v_pk_fma_f32 v[164:165], v[104:105], v[218:219], v[184:185]
	v_pk_fma_f32 v[104:105], v[124:125], v[220:221], v[188:189]
	v_pk_fma_f32 v[124:125], v[126:127], v[168:169], v[190:191]
	v_pk_fma_f32 v[116:117], v[116:117], v[222:223], v[192:193]
	v_pk_fma_f32 v[118:119], v[118:119], v[170:171], v[194:195]
	v_cvt_pk_bf16_f32 v108, v112, v113
	v_cvt_pk_bf16_f32 v109, v114, v115
	v_cvt_pk_bf16_f32 v110, v160, v161
	v_cvt_pk_bf16_f32 v111, v162, v163
	v_and_b32_e32 v167, 0xffff0000, v167
	v_cvt_pk_bf16_f32 v112, v104, v105
	v_cvt_pk_bf16_f32 v113, v124, v125
	v_cvt_pk_bf16_f32 v114, v116, v117
	v_cvt_pk_bf16_f32 v115, v118, v119
	global_store_dwordx4 v[210:211], v[108:111], off offset:256
	global_store_dwordx4 v[210:211], v[112:115], off
	v_pk_fma_f32 v[120:121], v[120:121], v[216:217], v[180:181]
	v_pk_fma_f32 v[108:109], v[106:107], v[166:167], v[186:187]
	v_cvt_pk_bf16_f32 v104, v120, v121
	v_cvt_pk_bf16_f32 v107, v108, v109
	v_lshl_add_u64 v[108:109], s[14:15], 0, v[208:209]
	v_cvt_pk_bf16_f32 v105, v122, v123
	v_cvt_pk_bf16_f32 v106, v164, v165
	v_lshl_add_u64 v[108:109], v[108:109], 0, v[146:147]
	global_store_dwordx4 v[108:109], v[104:107], off
	v_or_b32_e32 v176, 32, v148
	v_ashrrev_i32_e32 v177, 31, v176
	v_lshlrev_b32_e32 v104, 16, v196
	v_and_b32_e32 v105, 0xffff0000, v196
	v_pk_fma_f32 v[100:101], v[100:101], v[104:105], v[200:201]
	v_lshlrev_b32_e32 v104, 16, v197
	v_and_b32_e32 v105, 0xffff0000, v197
	v_pk_fma_f32 v[104:105], v[102:103], v[104:105], v[202:203]
	v_lshlrev_b32_e32 v102, 16, v198
	v_and_b32_e32 v103, 0xffff0000, v198
	v_pk_fma_f32 v[106:107], v[96:97], v[102:103], v[204:205]
	v_lshlrev_b32_e32 v96, 16, v199
	v_and_b32_e32 v97, 0xffff0000, v199
	v_pk_fma_f32 v[110:111], v[98:99], v[96:97], v[206:207]
	v_mad_i64_i32 v[98:99], s[56:57], v176, s74, v[150:151]
	v_lshl_add_u64 v[112:113], v[98:99], 0, v[146:147]
	v_add_co_u32_e32 v98, vcc, s67, v112
	v_cvt_pk_bf16_f32 v96, v100, v101
	s_nop 0
	v_addc_co_u32_e32 v99, vcc, 0, v113, vcc
	global_load_dwordx4 v[100:103], v[98:99], off offset:3072 nt
	v_cvt_pk_bf16_f32 v97, v104, v105
	v_cvt_pk_bf16_f32 v98, v106, v107
	v_cvt_pk_bf16_f32 v99, v110, v111
	v_lshlrev_b64 v[104:105], 13, v[176:177]
	global_store_dwordx4 v[108:109], v[96:99], off offset:256
	v_lshl_add_u64 v[116:117], v[152:153], 0, v[104:105]
	v_or_b32_e32 v178, 48, v148
	v_lshl_add_u64 v[96:97], v[112:113], 0, s[20:21]
	global_load_dwordx4 v[96:99], v[96:97], off offset:256 nt
	s_nop 0
	global_load_dwordx4 v[104:107], v[116:117], off
	global_load_dwordx4 v[108:111], v[116:117], off offset:16
	global_load_dwordx4 v[112:115], v[116:117], off offset:512
	s_nop 0
	global_load_dwordx4 v[116:119], v[116:117], off offset:528
	v_mad_i64_i32 v[120:121], s[56:57], v178, s74, v[150:151]
	v_lshl_add_u64 v[164:165], v[120:121], 0, v[146:147]
	v_add_co_u32_e32 v120, vcc, s67, v164
	v_ashrrev_i32_e32 v179, 31, v178
	s_nop 0
	v_addc_co_u32_e32 v121, vcc, 0, v165, vcc
	v_lshlrev_b64 v[124:125], 13, v[178:179]
	global_load_dwordx4 v[120:123], v[120:121], off offset:3072 nt
	v_lshl_add_u64 v[172:173], v[152:153], 0, v[124:125]
	global_load_dwordx4 v[124:127], v[172:173], off
	global_load_dwordx4 v[160:163], v[172:173], off offset:16
	v_lshl_add_u64 v[164:165], v[164:165], 0, s[20:21]
	global_load_dwordx4 v[164:167], v[164:165], off offset:256 nt
	s_nop 0
	global_load_dwordx4 v[168:171], v[172:173], off offset:512
	s_nop 0
	global_load_dwordx4 v[172:175], v[172:173], off offset:528
	v_lshlrev_b64 v[176:177], 12, v[176:177]
	v_lshl_add_u64 v[176:177], s[14:15], 0, v[176:177]
	v_lshl_add_u64 v[176:177], v[176:177], 0, v[146:147]
	s_waitcnt vmcnt(12)
	v_lshlrev_b32_e32 v180, 16, v100
	v_and_b32_e32 v181, 0xffff0000, v100
	v_lshlrev_b32_e32 v100, 16, v101
	v_and_b32_e32 v101, 0xffff0000, v101
	v_lshlrev_b32_e32 v182, 16, v102
	v_and_b32_e32 v183, 0xffff0000, v102
	v_lshlrev_b32_e32 v102, 16, v103
	v_and_b32_e32 v103, 0xffff0000, v103
	s_waitcnt vmcnt(9)
	v_pk_fma_f32 v[92:93], v[92:93], v[180:181], v[104:105]
	v_pk_fma_f32 v[94:95], v[94:95], v[100:101], v[106:107]
	s_waitcnt vmcnt(8)
	v_pk_fma_f32 v[100:101], v[88:89], v[182:183], v[108:109]
	v_pk_fma_f32 v[102:103], v[90:91], v[102:103], v[110:111]
	v_cvt_pk_bf16_f32 v88, v92, v93
	v_cvt_pk_bf16_f32 v89, v94, v95
	v_cvt_pk_bf16_f32 v90, v100, v101
	v_cvt_pk_bf16_f32 v91, v102, v103
	global_store_dwordx4 v[176:177], v[88:91], off
	v_lshlrev_b32_e32 v184, 16, v96
	v_and_b32_e32 v185, 0xffff0000, v96
	v_lshlrev_b32_e32 v88, 16, v97
	v_and_b32_e32 v89, 0xffff0000, v97
	s_waitcnt vmcnt(8)
	v_pk_fma_f32 v[86:87], v[86:87], v[88:89], v[114:115]
	v_lshlrev_b32_e32 v88, 16, v98
	v_and_b32_e32 v89, 0xffff0000, v98
	s_waitcnt vmcnt(7)
	v_pk_fma_f32 v[88:89], v[76:77], v[88:89], v[116:117]
	v_lshlrev_b32_e32 v76, 16, v99
	v_and_b32_e32 v77, 0xffff0000, v99
	v_pk_fma_f32 v[84:85], v[84:85], v[184:185], v[112:113]
	v_pk_fma_f32 v[90:91], v[78:79], v[76:77], v[118:119]
	v_cvt_pk_bf16_f32 v76, v84, v85
	v_cvt_pk_bf16_f32 v77, v86, v87
	v_cvt_pk_bf16_f32 v78, v88, v89
	v_cvt_pk_bf16_f32 v79, v90, v91
	global_store_dwordx4 v[176:177], v[76:79], off offset:256
	v_add_u32_e32 v112, 0x80, v148
	v_ashrrev_i32_e32 v113, 31, v112
	s_waitcnt vmcnt(7)
	v_lshlrev_b32_e32 v78, 16, v120
	v_and_b32_e32 v79, 0xffff0000, v120
	s_waitcnt vmcnt(6)
	v_pk_fma_f32 v[78:79], v[80:81], v[78:79], v[124:125]
	v_lshlrev_b32_e32 v80, 16, v121
	v_and_b32_e32 v81, 0xffff0000, v121
	v_pk_fma_f32 v[80:81], v[82:83], v[80:81], v[126:127]
	v_lshlrev_b32_e32 v82, 16, v122
	v_and_b32_e32 v83, 0xffff0000, v122
	v_lshlrev_b64 v[76:77], 12, v[178:179]
	s_waitcnt vmcnt(5)
	v_pk_fma_f32 v[82:83], v[72:73], v[82:83], v[160:161]
	v_lshlrev_b32_e32 v72, 16, v123
	v_and_b32_e32 v73, 0xffff0000, v123
	v_pk_fma_f32 v[84:85], v[74:75], v[72:73], v[162:163]
	v_lshl_add_u64 v[76:77], s[14:15], 0, v[76:77]
	v_cvt_pk_bf16_f32 v72, v78, v79
	v_cvt_pk_bf16_f32 v73, v80, v81
	v_cvt_pk_bf16_f32 v74, v82, v83
	v_cvt_pk_bf16_f32 v75, v84, v85
	v_lshl_add_u64 v[76:77], v[76:77], 0, v[146:147]
	global_store_dwordx4 v[76:77], v[72:75], off
	v_add_u32_e32 v114, 0x90, v148
	v_mad_i64_i32 v[88:89], s[56:57], v114, s74, v[150:151]
	s_waitcnt vmcnt(5)
	v_lshlrev_b32_e32 v72, 16, v164
	v_and_b32_e32 v73, 0xffff0000, v164
	s_waitcnt vmcnt(4)
	v_pk_fma_f32 v[68:69], v[68:69], v[72:73], v[168:169]
	v_lshlrev_b32_e32 v72, 16, v165
	v_and_b32_e32 v73, 0xffff0000, v165
	v_pk_fma_f32 v[70:71], v[70:71], v[72:73], v[170:171]
	v_lshlrev_b32_e32 v72, 16, v166
	v_and_b32_e32 v73, 0xffff0000, v166
	s_waitcnt vmcnt(3)
	v_pk_fma_f32 v[72:73], v[64:65], v[72:73], v[172:173]
	v_lshlrev_b32_e32 v64, 16, v167
	v_and_b32_e32 v65, 0xffff0000, v167
	v_pk_fma_f32 v[74:75], v[66:67], v[64:65], v[174:175]
	v_cvt_pk_bf16_f32 v64, v68, v69
	v_cvt_pk_bf16_f32 v65, v70, v71
	v_cvt_pk_bf16_f32 v66, v72, v73
	v_cvt_pk_bf16_f32 v67, v74, v75
	global_store_dwordx4 v[76:77], v[64:67], off offset:256
	v_lshlrev_b64 v[68:69], 13, v[112:113]
	v_lshl_add_u64 v[84:85], v[152:153], 0, v[68:69]
	v_mad_i64_i32 v[64:65], s[56:57], v112, s74, v[150:151]
	v_lshl_add_u64 v[76:77], v[64:65], 0, v[146:147]
	v_add_co_u32_e32 v64, vcc, s67, v76
	v_lshl_add_u64 v[100:101], v[88:89], 0, v[146:147]
	s_nop 0
	v_addc_co_u32_e32 v65, vcc, 0, v77, vcc
	global_load_dwordx4 v[64:67], v[64:65], off offset:3072 nt
	s_nop 0
	global_load_dwordx4 v[68:71], v[84:85], off
	global_load_dwordx4 v[72:75], v[84:85], off offset:16
	v_lshl_add_u64 v[76:77], v[76:77], 0, s[20:21]
	global_load_dwordx4 v[76:79], v[76:77], off offset:256 nt
	s_nop 0
	global_load_dwordx4 v[80:83], v[84:85], off offset:512
	s_nop 0
	global_load_dwordx4 v[84:87], v[84:85], off offset:528
	v_add_co_u32_e32 v88, vcc, s67, v100
	v_ashrrev_i32_e32 v115, 31, v114
	s_nop 0
	v_addc_co_u32_e32 v89, vcc, 0, v101, vcc
	v_lshlrev_b64 v[92:93], 13, v[114:115]
	global_load_dwordx4 v[88:91], v[88:89], off offset:3072 nt
	v_lshl_add_u64 v[108:109], v[152:153], 0, v[92:93]
	global_load_dwordx4 v[92:95], v[108:109], off
	global_load_dwordx4 v[96:99], v[108:109], off offset:16
	v_lshl_add_u64 v[100:101], v[100:101], 0, s[20:21]
	global_load_dwordx4 v[100:103], v[100:101], off offset:256 nt
	s_nop 0
	global_load_dwordx4 v[104:107], v[108:109], off offset:512
	s_nop 0
	global_load_dwordx4 v[108:111], v[108:109], off offset:528
	v_lshlrev_b64 v[112:113], 12, v[112:113]
	s_waitcnt vmcnt(11)
	v_lshlrev_b32_e32 v116, 16, v64
	v_and_b32_e32 v117, 0xffff0000, v64
	v_lshlrev_b32_e32 v64, 16, v65
	v_and_b32_e32 v65, 0xffff0000, v65
	s_waitcnt vmcnt(10)
	v_pk_fma_f32 v[62:63], v[62:63], v[64:65], v[70:71]
	v_lshlrev_b32_e32 v64, 16, v66
	v_and_b32_e32 v65, 0xffff0000, v66
	v_pk_fma_f32 v[60:61], v[60:61], v[116:117], v[68:69]
	s_waitcnt vmcnt(9)
	v_pk_fma_f32 v[64:65], v[56:57], v[64:65], v[72:73]
	v_lshlrev_b32_e32 v56, 16, v67
	v_and_b32_e32 v57, 0xffff0000, v67
	v_pk_fma_f32 v[66:67], v[58:59], v[56:57], v[74:75]
	v_cvt_pk_bf16_f32 v56, v60, v61
	v_lshl_add_u64 v[60:61], s[14:15], 0, v[112:113]
	v_cvt_pk_bf16_f32 v57, v62, v63
	v_cvt_pk_bf16_f32 v58, v64, v65
	v_cvt_pk_bf16_f32 v59, v66, v67
	v_lshl_add_u64 v[60:61], v[60:61], 0, v[146:147]
	global_store_dwordx4 v[60:61], v[56:59], off
	s_waitcnt vmcnt(9)
	s_nop 0
	v_lshlrev_b32_e32 v56, 16, v76
	v_and_b32_e32 v57, 0xffff0000, v76
	s_waitcnt vmcnt(8)
	v_pk_fma_f32 v[52:53], v[52:53], v[56:57], v[80:81]
	v_lshlrev_b32_e32 v56, 16, v77
	v_and_b32_e32 v57, 0xffff0000, v77
	v_pk_fma_f32 v[54:55], v[54:55], v[56:57], v[82:83]
	v_lshlrev_b32_e32 v56, 16, v78
	v_and_b32_e32 v57, 0xffff0000, v78
	s_waitcnt vmcnt(7)
	v_pk_fma_f32 v[56:57], v[44:45], v[56:57], v[84:85]
	v_lshlrev_b32_e32 v44, 16, v79
	v_and_b32_e32 v45, 0xffff0000, v79
	v_pk_fma_f32 v[58:59], v[46:47], v[44:45], v[86:87]
	v_cvt_pk_bf16_f32 v44, v52, v53
	v_cvt_pk_bf16_f32 v45, v54, v55
	v_cvt_pk_bf16_f32 v46, v56, v57
	v_cvt_pk_bf16_f32 v47, v58, v59
	global_store_dwordx4 v[60:61], v[44:47], off offset:256
	v_add_u32_e32 v80, 0xa0, v148
	v_ashrrev_i32_e32 v81, 31, v80
	s_waitcnt vmcnt(7)
	v_lshlrev_b32_e32 v46, 16, v88
	v_and_b32_e32 v47, 0xffff0000, v88
	s_waitcnt vmcnt(6)
	v_pk_fma_f32 v[46:47], v[48:49], v[46:47], v[92:93]
	v_lshlrev_b32_e32 v48, 16, v89
	v_and_b32_e32 v49, 0xffff0000, v89
	v_pk_fma_f32 v[48:49], v[50:51], v[48:49], v[94:95]
	v_lshlrev_b32_e32 v50, 16, v90
	v_and_b32_e32 v51, 0xffff0000, v90
	v_lshlrev_b64 v[44:45], 12, v[114:115]
	s_waitcnt vmcnt(5)
	v_pk_fma_f32 v[50:51], v[40:41], v[50:51], v[96:97]
	v_lshlrev_b32_e32 v40, 16, v91
	v_and_b32_e32 v41, 0xffff0000, v91
	v_pk_fma_f32 v[52:53], v[42:43], v[40:41], v[98:99]
	v_lshl_add_u64 v[44:45], s[14:15], 0, v[44:45]
	v_cvt_pk_bf16_f32 v40, v46, v47
	v_cvt_pk_bf16_f32 v41, v48, v49
	v_cvt_pk_bf16_f32 v42, v50, v51
	v_cvt_pk_bf16_f32 v43, v52, v53
	v_lshl_add_u64 v[44:45], v[44:45], 0, v[146:147]
	global_store_dwordx4 v[44:45], v[40:43], off
	v_add_u32_e32 v82, 0xb0, v148
	v_mad_i64_i32 v[56:57], s[56:57], v82, s74, v[150:151]
	s_waitcnt vmcnt(5)
	v_lshlrev_b32_e32 v40, 16, v100
	v_and_b32_e32 v41, 0xffff0000, v100
	s_waitcnt vmcnt(4)
	v_pk_fma_f32 v[36:37], v[36:37], v[40:41], v[104:105]
	v_lshlrev_b32_e32 v40, 16, v101
	v_and_b32_e32 v41, 0xffff0000, v101
	v_pk_fma_f32 v[38:39], v[38:39], v[40:41], v[106:107]
	v_lshlrev_b32_e32 v40, 16, v102
	v_and_b32_e32 v41, 0xffff0000, v102
	s_waitcnt vmcnt(3)
	v_pk_fma_f32 v[40:41], v[32:33], v[40:41], v[108:109]
	v_lshlrev_b32_e32 v32, 16, v103
	v_and_b32_e32 v33, 0xffff0000, v103
	v_pk_fma_f32 v[42:43], v[34:35], v[32:33], v[110:111]
	v_cvt_pk_bf16_f32 v32, v36, v37
	v_cvt_pk_bf16_f32 v33, v38, v39
	v_cvt_pk_bf16_f32 v34, v40, v41
	v_cvt_pk_bf16_f32 v35, v42, v43
	global_store_dwordx4 v[44:45], v[32:35], off offset:256
	v_lshlrev_b64 v[36:37], 13, v[80:81]
	v_lshl_add_u64 v[52:53], v[152:153], 0, v[36:37]
	v_mad_i64_i32 v[32:33], s[56:57], v80, s74, v[150:151]
	v_lshl_add_u64 v[44:45], v[32:33], 0, v[146:147]
	v_add_co_u32_e32 v32, vcc, s67, v44
	v_lshl_add_u64 v[68:69], v[56:57], 0, v[146:147]
	s_nop 0
	v_addc_co_u32_e32 v33, vcc, 0, v45, vcc
	global_load_dwordx4 v[32:35], v[32:33], off offset:3072 nt
	s_nop 0
	global_load_dwordx4 v[36:39], v[52:53], off
	global_load_dwordx4 v[40:43], v[52:53], off offset:16
	v_lshl_add_u64 v[44:45], v[44:45], 0, s[20:21]
	global_load_dwordx4 v[44:47], v[44:45], off offset:256 nt
	s_nop 0
	global_load_dwordx4 v[48:51], v[52:53], off offset:512
	s_nop 0
	global_load_dwordx4 v[52:55], v[52:53], off offset:528
	v_add_co_u32_e32 v56, vcc, s67, v68
	v_ashrrev_i32_e32 v83, 31, v82
	s_nop 0
	v_addc_co_u32_e32 v57, vcc, 0, v69, vcc
	v_lshlrev_b64 v[60:61], 13, v[82:83]
	global_load_dwordx4 v[56:59], v[56:57], off offset:3072 nt
	v_lshl_add_u64 v[76:77], v[152:153], 0, v[60:61]
	global_load_dwordx4 v[60:63], v[76:77], off
	global_load_dwordx4 v[64:67], v[76:77], off offset:16
	v_lshl_add_u64 v[68:69], v[68:69], 0, s[20:21]
	global_load_dwordx4 v[68:71], v[68:69], off offset:256 nt
	s_nop 0
	global_load_dwordx4 v[72:75], v[76:77], off offset:512
	s_nop 0
	global_load_dwordx4 v[76:79], v[76:77], off offset:528
	v_lshlrev_b64 v[80:81], 12, v[80:81]
	s_andn2_b64 vcc, exec, s[4:5]
	s_mov_b64 s[4:5], -1
	s_waitcnt vmcnt(11)
	v_lshlrev_b32_e32 v84, 16, v32
	v_and_b32_e32 v85, 0xffff0000, v32
	v_lshlrev_b32_e32 v32, 16, v33
	v_and_b32_e32 v33, 0xffff0000, v33
	s_waitcnt vmcnt(10)
	v_pk_fma_f32 v[30:31], v[30:31], v[32:33], v[38:39]
	v_lshlrev_b32_e32 v32, 16, v34
	v_and_b32_e32 v33, 0xffff0000, v34
	v_pk_fma_f32 v[28:29], v[28:29], v[84:85], v[36:37]
	s_waitcnt vmcnt(9)
	v_pk_fma_f32 v[32:33], v[24:25], v[32:33], v[40:41]
	v_lshlrev_b32_e32 v24, 16, v35
	v_and_b32_e32 v25, 0xffff0000, v35
	v_pk_fma_f32 v[34:35], v[26:27], v[24:25], v[42:43]
	v_cvt_pk_bf16_f32 v24, v28, v29
	v_lshl_add_u64 v[28:29], s[14:15], 0, v[80:81]
	v_cvt_pk_bf16_f32 v25, v30, v31
	v_cvt_pk_bf16_f32 v26, v32, v33
	v_cvt_pk_bf16_f32 v27, v34, v35
	v_lshl_add_u64 v[28:29], v[28:29], 0, v[146:147]
	global_store_dwordx4 v[28:29], v[24:27], off
	s_waitcnt vmcnt(9)
	s_nop 0
	v_lshlrev_b32_e32 v24, 16, v44
	v_and_b32_e32 v25, 0xffff0000, v44
	s_waitcnt vmcnt(8)
	v_pk_fma_f32 v[20:21], v[20:21], v[24:25], v[48:49]
	v_lshlrev_b32_e32 v24, 16, v45
	v_and_b32_e32 v25, 0xffff0000, v45
	v_pk_fma_f32 v[22:23], v[22:23], v[24:25], v[50:51]
	v_lshlrev_b32_e32 v24, 16, v46
	v_and_b32_e32 v25, 0xffff0000, v46
	s_waitcnt vmcnt(7)
	v_pk_fma_f32 v[24:25], v[12:13], v[24:25], v[52:53]
	v_lshlrev_b32_e32 v12, 16, v47
	v_and_b32_e32 v13, 0xffff0000, v47
	v_pk_fma_f32 v[26:27], v[14:15], v[12:13], v[54:55]
	v_cvt_pk_bf16_f32 v12, v20, v21
	v_cvt_pk_bf16_f32 v13, v22, v23
	v_cvt_pk_bf16_f32 v14, v24, v25
	v_cvt_pk_bf16_f32 v15, v26, v27
	global_store_dwordx4 v[28:29], v[12:15], off offset:256
	s_waitcnt vmcnt(7)
	s_nop 0
	v_lshlrev_b32_e32 v14, 16, v56
	v_and_b32_e32 v15, 0xffff0000, v56
	s_waitcnt vmcnt(6)
	v_pk_fma_f32 v[14:15], v[16:17], v[14:15], v[60:61]
	v_lshlrev_b32_e32 v16, 16, v57
	v_and_b32_e32 v17, 0xffff0000, v57
	v_pk_fma_f32 v[16:17], v[18:19], v[16:17], v[62:63]
	v_lshlrev_b32_e32 v18, 16, v58
	v_and_b32_e32 v19, 0xffff0000, v58
	v_lshlrev_b64 v[12:13], 12, v[82:83]
	s_waitcnt vmcnt(5)
	v_pk_fma_f32 v[18:19], v[8:9], v[18:19], v[64:65]
	v_lshlrev_b32_e32 v8, 16, v59
	v_and_b32_e32 v9, 0xffff0000, v59
	v_pk_fma_f32 v[20:21], v[10:11], v[8:9], v[66:67]
	v_lshl_add_u64 v[12:13], s[14:15], 0, v[12:13]
	v_cvt_pk_bf16_f32 v8, v14, v15
	v_cvt_pk_bf16_f32 v9, v16, v17
	v_cvt_pk_bf16_f32 v10, v18, v19
	v_cvt_pk_bf16_f32 v11, v20, v21
	v_lshl_add_u64 v[12:13], v[12:13], 0, v[146:147]
	global_store_dwordx4 v[12:13], v[8:11], off
	s_waitcnt vmcnt(5)
	s_nop 0
	v_lshlrev_b32_e32 v8, 16, v68
	v_and_b32_e32 v9, 0xffff0000, v68
	s_waitcnt vmcnt(4)
	v_pk_fma_f32 v[4:5], v[4:5], v[8:9], v[72:73]
	v_lshlrev_b32_e32 v8, 16, v69
	v_and_b32_e32 v9, 0xffff0000, v69
	v_pk_fma_f32 v[6:7], v[6:7], v[8:9], v[74:75]
	v_lshlrev_b32_e32 v8, 16, v70
	v_and_b32_e32 v9, 0xffff0000, v70
	s_waitcnt vmcnt(3)
	v_pk_fma_f32 v[8:9], v[0:1], v[8:9], v[76:77]
	v_lshlrev_b32_e32 v0, 16, v71
	v_and_b32_e32 v1, 0xffff0000, v71
	v_pk_fma_f32 v[10:11], v[2:3], v[0:1], v[78:79]
	v_cvt_pk_bf16_f32 v0, v4, v5
	v_cvt_pk_bf16_f32 v1, v6, v7
	v_cvt_pk_bf16_f32 v2, v8, v9
	v_cvt_pk_bf16_f32 v3, v10, v11
	global_store_dwordx4 v[12:13], v[0:3], off offset:256
	s_cbranch_vccnz .LBB0_1402
	s_andn2_b64 vcc, exec, s[12:13]
	s_cbranch_vccnz .LBB0_1401
	s_barrier
	s_branch .LBB0_1401

.LBB0_1625:
	s_mov_b64 s[80:81], exec
	s_mov_b64 exec, 1
	v_mov_b32_e32 v237, 1
	global_atomic_add v237, v236, v237, s[50:51] sc0
	s_mov_b64 exec, s[80:81]
	global_load_dwordx4 v[28:31], v[136:137], off offset:-4096
	global_load_dwordx4 v[24:27], v[136:137], off offset:-3072
	global_load_dwordx4 v[20:23], v[136:137], off offset:-2048
	global_load_dwordx4 v[16:19], v[136:137], off offset:-1024
	global_load_dwordx4 v[12:15], v[136:137], off
	global_load_dwordx4 v[8:11], v[136:137], off offset:1024
	global_load_dwordx4 v[4:7], v[136:137], off offset:2048
	global_load_dwordx4 v[0:3], v[136:137], off offset:3072
	v_add_u32_e32 v33, 0xffffe000, v130
	v_lshrrev_b32_e32 v33, 3, v33
	v_ashrrev_i32_e32 v32, 12, v130
	v_add_u32_e32 v33, 2, v33
	v_cmp_gt_i32_e32 vcc, s3, v130
	s_nop 1
	v_cndmask_b32_e32 v32, v33, v32, vcc
	v_mad_i64_i32 v[64:65], s[26:27], v32, s18, v[138:139]
	v_add_co_u32_e32 v50, vcc, s19, v134
	v_lshl_add_u64 v[48:49], v[64:65], 0, s[12:13]
	s_nop 0
	v_addc_co_u32_e32 v51, vcc, -1, v135, vcc
	v_add_co_u32_e32 v60, vcc, s20, v134
	v_lshl_add_u64 v[40:41], v[48:49], 0, v[132:133]
	s_nop 0
	v_addc_co_u32_e32 v61, vcc, -1, v135, vcc
	v_add_co_u32_e32 v62, vcc, s21, v134
	v_lshl_add_u64 v[42:43], v[48:49], 0, v[140:141]
	v_lshl_add_u64 v[52:53], v[48:49], 0, v[142:143]
	v_lshl_add_u64 v[54:55], v[48:49], 0, v[144:145]
	v_addc_co_u32_e32 v63, vcc, -1, v135, vcc
	global_load_dwordx4 v[36:39], v[40:41], off
	global_load_dwordx4 v[32:35], v[42:43], off
	global_load_dwordx2 v[82:83], v[50:51], off offset:-3584 nt
	global_load_dwordx2 v[84:85], v[50:51], off offset:-3072 nt
	global_load_dwordx2 v[86:87], v[50:51], off offset:-2560 nt
	global_load_dwordx2 v[88:89], v[50:51], off offset:-2048 nt
	global_load_dwordx2 v[90:91], v[60:61], off offset:-3584 nt
	global_load_dwordx2 v[92:93], v[60:61], off offset:-3072 nt
	global_load_dwordx2 v[94:95], v[60:61], off offset:-2560 nt
	global_load_dwordx2 v[96:97], v[60:61], off offset:-2048 nt
	global_load_dwordx2 v[98:99], v[62:63], off offset:-3584 nt
	global_load_dwordx2 v[100:101], v[62:63], off offset:-3072 nt
	global_load_dwordx2 v[102:103], v[62:63], off offset:-2560 nt
	global_load_dwordx2 v[104:105], v[62:63], off offset:-2048 nt
	global_load_dwordx2 v[106:107], v[134:135], off offset:-3584 nt
	global_load_dwordx2 v[108:109], v[134:135], off offset:-3072 nt
	global_load_dwordx2 v[110:111], v[134:135], off offset:-2560 nt
	global_load_dwordx2 v[112:113], v[134:135], off offset:-2048 nt
	global_load_dwordx4 v[44:47], v[52:53], off
	global_load_dwordx4 v[40:43], v[54:55], off
	v_lshl_add_u64 v[52:53], v[48:49], 0, v[146:147]
	v_lshl_add_u64 v[54:55], v[48:49], 0, v[148:149]
	global_load_dwordx4 v[56:59], v[52:53], off
	s_nop 0
	global_load_dwordx4 v[52:55], v[54:55], off
	s_nop 0
	global_load_dwordx2 v[116:117], v[50:51], off offset:-1536 nt
	global_load_dwordx2 v[118:119], v[50:51], off offset:-1024 nt
	global_load_dwordx2 v[74:75], v[50:51], off offset:-512 nt
	global_load_dwordx2 v[70:71], v[50:51], off nt
	global_load_dwordx2 v[120:121], v[60:61], off offset:-1536 nt
	global_load_dwordx2 v[122:123], v[60:61], off offset:-1024 nt
	global_load_dwordx2 v[80:81], v[60:61], off offset:-512 nt
	global_load_dwordx2 v[72:73], v[60:61], off nt
	global_load_dwordx2 v[124:125], v[62:63], off offset:-1536 nt
	global_load_dwordx2 v[126:127], v[62:63], off offset:-1024 nt
	global_load_dwordx2 v[76:77], v[62:63], off offset:-512 nt
	global_load_dwordx2 v[66:67], v[62:63], off nt
	global_load_dwordx2 v[172:173], v[134:135], off offset:-1536 nt
	global_load_dwordx2 v[178:179], v[134:135], off offset:-1024 nt
	global_load_dwordx2 v[78:79], v[134:135], off offset:-512 nt
	global_load_dwordx2 v[68:69], v[134:135], off nt
	v_lshl_add_u64 v[114:115], v[48:49], 0, v[150:151]
	v_lshl_add_u64 v[48:49], v[48:49], 0, v[152:153]
	global_load_dwordx4 v[60:63], v[114:115], off
	s_nop 0
	global_load_dwordx4 v[48:51], v[48:49], off
	s_waitcnt vmcnt(37)
	v_lshlrev_b32_e32 v114, 16, v82
	v_and_b32_e32 v115, 0xffff0000, v82
	s_waitcnt vmcnt(33)
	v_lshlrev_b32_e32 v154, 16, v90
	v_and_b32_e32 v155, 0xffff0000, v90
	v_lshlrev_b32_e32 v82, 16, v83
	v_and_b32_e32 v83, 0xffff0000, v83
	v_lshlrev_b32_e32 v90, 16, v91
	v_and_b32_e32 v91, 0xffff0000, v91
	v_pk_add_f32 v[114:115], v[114:115], v[154:155]
	s_waitcnt vmcnt(29)
	v_lshlrev_b32_e32 v154, 16, v98
	v_and_b32_e32 v155, 0xffff0000, v98
	v_pk_add_f32 v[82:83], v[82:83], v[90:91]
	v_lshlrev_b32_e32 v90, 16, v99
	v_and_b32_e32 v91, 0xffff0000, v99
	s_waitcnt vmcnt(25)
	v_lshlrev_b32_e32 v98, 16, v107
	v_and_b32_e32 v99, 0xffff0000, v107
	v_lshlrev_b32_e32 v156, 16, v106
	v_and_b32_e32 v157, 0xffff0000, v106
	v_pk_add_f32 v[90:91], v[90:91], v[98:99]
	v_pk_add_f32 v[154:155], v[154:155], v[156:157]
	v_pk_add_f32 v[156:157], v[82:83], v[90:91]
	v_lshlrev_b32_e32 v82, 16, v84
	v_and_b32_e32 v83, 0xffff0000, v84
	v_lshlrev_b32_e32 v90, 16, v92
	v_and_b32_e32 v91, 0xffff0000, v92
	v_pk_add_f32 v[82:83], v[82:83], v[90:91]
	v_lshlrev_b32_e32 v90, 16, v100
	v_and_b32_e32 v91, 0xffff0000, v100
	s_waitcnt vmcnt(24)
	v_lshlrev_b32_e32 v98, 16, v108
	v_and_b32_e32 v99, 0xffff0000, v108
	v_pk_add_f32 v[90:91], v[90:91], v[98:99]
	v_lshlrev_b32_e32 v84, 16, v93
	v_pk_add_f32 v[158:159], v[82:83], v[90:91]
	v_lshlrev_b32_e32 v82, 16, v85
	v_and_b32_e32 v83, 0xffff0000, v85
	v_and_b32_e32 v85, 0xffff0000, v93
	v_pk_add_f32 v[82:83], v[82:83], v[84:85]
	v_lshlrev_b32_e32 v84, 16, v101
	v_and_b32_e32 v85, 0xffff0000, v101
	v_lshlrev_b32_e32 v90, 16, v109
	v_and_b32_e32 v91, 0xffff0000, v109
	v_pk_add_f32 v[84:85], v[84:85], v[90:91]
	s_waitcnt vmcnt(23)
	v_lshlrev_b32_e32 v90, 16, v110
	v_pk_add_f32 v[160:161], v[82:83], v[84:85]
	v_lshlrev_b32_e32 v82, 16, v86
	v_and_b32_e32 v83, 0xffff0000, v86
	v_lshlrev_b32_e32 v84, 16, v94
	v_and_b32_e32 v85, 0xffff0000, v94
	v_pk_add_f32 v[82:83], v[82:83], v[84:85]
	v_lshlrev_b32_e32 v84, 16, v102
	v_and_b32_e32 v85, 0xffff0000, v102
	v_and_b32_e32 v91, 0xffff0000, v110
	v_pk_add_f32 v[84:85], v[84:85], v[90:91]
	v_lshlrev_b32_e32 v86, 16, v111
	v_pk_add_f32 v[162:163], v[82:83], v[84:85]
	v_lshlrev_b32_e32 v82, 16, v87
	v_and_b32_e32 v83, 0xffff0000, v87
	v_lshlrev_b32_e32 v84, 16, v95
	v_and_b32_e32 v85, 0xffff0000, v95
	v_pk_add_f32 v[82:83], v[82:83], v[84:85]
	v_lshlrev_b32_e32 v84, 16, v103
	v_and_b32_e32 v85, 0xffff0000, v103
	v_and_b32_e32 v87, 0xffff0000, v111
	v_pk_add_f32 v[84:85], v[84:85], v[86:87]
	s_waitcnt vmcnt(22)
	v_lshlrev_b32_e32 v86, 16, v112
	v_pk_add_f32 v[164:165], v[82:83], v[84:85]
	v_mov_b32_e32 v84, v163
	v_mov_b32_e32 v85, v165
	v_mov_b32_e32 v82, v162
	v_mov_b32_e32 v83, v164
	v_pk_mul_f32 v[84:85], v[84:85], v[84:85]
	v_and_b32_e32 v87, 0xffff0000, v112
	v_pk_fma_f32 v[82:83], v[82:83], v[82:83], v[84:85]
	v_lshlrev_b32_e32 v84, 16, v96
	v_pk_add_f32 v[176:177], v[82:83], v[82:83] op_sel:[0,1] op_sel_hi:[1,0]
	v_lshlrev_b32_e32 v82, 16, v88
	v_and_b32_e32 v83, 0xffff0000, v88
	v_and_b32_e32 v85, 0xffff0000, v96
	v_pk_add_f32 v[82:83], v[82:83], v[84:85]
	v_lshlrev_b32_e32 v84, 16, v104
	v_and_b32_e32 v85, 0xffff0000, v104
	v_pk_add_f32 v[84:85], v[84:85], v[86:87]
	v_lshlrev_b32_e32 v86, 16, v113
	v_pk_add_f32 v[166:167], v[82:83], v[84:85]
	v_lshlrev_b32_e32 v82, 16, v89
	v_and_b32_e32 v83, 0xffff0000, v89
	v_lshlrev_b32_e32 v84, 16, v97
	v_and_b32_e32 v85, 0xffff0000, v97
	v_pk_add_f32 v[82:83], v[82:83], v[84:85]
	v_lshlrev_b32_e32 v84, 16, v105
	v_and_b32_e32 v85, 0xffff0000, v105
	v_and_b32_e32 v87, 0xffff0000, v113
	v_pk_add_f32 v[84:85], v[84:85], v[86:87]
	s_waitcnt vmcnt(5)
	v_lshlrev_b32_e32 v86, 16, v172
	v_pk_add_f32 v[168:169], v[82:83], v[84:85]
	v_mul_f32_e32 v82, v167, v167
	v_pk_fma_f32 v[190:191], v[166:167], v[166:167], v[82:83] op_sel_hi:[1,1,0]
	v_mul_f32_e32 v82, v169, v169
	v_pk_fma_f32 v[192:193], v[168:169], v[168:169], v[82:83] op_sel_hi:[1,1,0]
	v_lshlrev_b32_e32 v82, 16, v116
	v_and_b32_e32 v83, 0xffff0000, v116
	v_lshlrev_b32_e32 v84, 16, v120
	v_and_b32_e32 v85, 0xffff0000, v120
	v_pk_add_f32 v[82:83], v[82:83], v[84:85]
	v_lshlrev_b32_e32 v84, 16, v124
	v_and_b32_e32 v85, 0xffff0000, v124
	v_and_b32_e32 v87, 0xffff0000, v172
	v_pk_add_f32 v[84:85], v[84:85], v[86:87]
	v_lshlrev_b32_e32 v86, 16, v173
	v_pk_add_f32 v[170:171], v[82:83], v[84:85]
	v_lshlrev_b32_e32 v82, 16, v117
	v_and_b32_e32 v83, 0xffff0000, v117
	v_lshlrev_b32_e32 v84, 16, v121
	v_and_b32_e32 v85, 0xffff0000, v121
	v_pk_add_f32 v[82:83], v[82:83], v[84:85]
	v_lshlrev_b32_e32 v84, 16, v125
	v_and_b32_e32 v85, 0xffff0000, v125
	v_and_b32_e32 v87, 0xffff0000, v173
	v_pk_add_f32 v[84:85], v[84:85], v[86:87]
	s_waitcnt vmcnt(4)
	v_lshlrev_b32_e32 v86, 16, v178
	v_pk_add_f32 v[172:173], v[82:83], v[84:85]
	v_lshlrev_b32_e32 v82, 16, v118
	v_and_b32_e32 v83, 0xffff0000, v118
	v_lshlrev_b32_e32 v84, 16, v122
	v_and_b32_e32 v85, 0xffff0000, v122
	v_pk_add_f32 v[82:83], v[82:83], v[84:85]
	v_lshlrev_b32_e32 v84, 16, v126
	v_and_b32_e32 v85, 0xffff0000, v126
	v_and_b32_e32 v87, 0xffff0000, v178
	v_pk_add_f32 v[84:85], v[84:85], v[86:87]
	v_lshlrev_b32_e32 v86, 16, v179
	v_pk_add_f32 v[174:175], v[82:83], v[84:85]
	v_lshlrev_b32_e32 v82, 16, v119
	v_and_b32_e32 v83, 0xffff0000, v119
	v_lshlrev_b32_e32 v84, 16, v123
	v_and_b32_e32 v85, 0xffff0000, v123
	v_pk_add_f32 v[82:83], v[82:83], v[84:85]
	v_lshlrev_b32_e32 v84, 16, v127
	v_and_b32_e32 v85, 0xffff0000, v127
	v_and_b32_e32 v87, 0xffff0000, v179
	v_pk_add_f32 v[84:85], v[84:85], v[86:87]
	s_waitcnt vmcnt(3)
	v_lshlrev_b32_e32 v86, 16, v78
	v_pk_add_f32 v[178:179], v[82:83], v[84:85]
	v_mov_b32_e32 v84, v175
	v_mov_b32_e32 v85, v179
	v_mov_b32_e32 v82, v174
	v_mov_b32_e32 v83, v178
	v_pk_mul_f32 v[84:85], v[84:85], v[84:85]
	v_and_b32_e32 v87, 0xffff0000, v78
	v_pk_fma_f32 v[82:83], v[82:83], v[82:83], v[84:85]
	v_lshlrev_b32_e32 v84, 16, v80
	v_pk_add_f32 v[198:199], v[82:83], v[82:83] op_sel:[0,1] op_sel_hi:[1,0]
	v_lshlrev_b32_e32 v82, 16, v74
	v_and_b32_e32 v83, 0xffff0000, v74
	v_and_b32_e32 v85, 0xffff0000, v80
	v_pk_add_f32 v[82:83], v[82:83], v[84:85]
	v_lshlrev_b32_e32 v84, 16, v76
	v_and_b32_e32 v85, 0xffff0000, v76
	v_pk_add_f32 v[84:85], v[84:85], v[86:87]
	v_lshlrev_b32_e32 v74, 16, v75
	v_and_b32_e32 v75, 0xffff0000, v75
	v_lshlrev_b32_e32 v80, 16, v81
	v_and_b32_e32 v81, 0xffff0000, v81
	v_lshlrev_b32_e32 v76, 16, v77
	v_and_b32_e32 v77, 0xffff0000, v77
	v_lshlrev_b32_e32 v78, 16, v79
	v_and_b32_e32 v79, 0xffff0000, v79
	v_pk_add_f32 v[180:181], v[82:83], v[84:85]
	v_pk_add_f32 v[74:75], v[74:75], v[80:81]
	v_pk_add_f32 v[76:77], v[76:77], v[78:79]
	s_waitcnt vmcnt(2)
	v_lshlrev_b32_e32 v78, 16, v68
	v_pk_add_f32 v[182:183], v[74:75], v[76:77]
	v_mul_f32_e32 v74, v181, v181
	v_pk_fma_f32 v[200:201], v[180:181], v[180:181], v[74:75] op_sel_hi:[1,1,0]
	v_mul_f32_e32 v74, v183, v183
	v_pk_fma_f32 v[202:203], v[182:183], v[182:183], v[74:75] op_sel_hi:[1,1,0]
	v_lshlrev_b32_e32 v74, 16, v70
	v_and_b32_e32 v75, 0xffff0000, v70
	v_lshlrev_b32_e32 v76, 16, v72
	v_and_b32_e32 v77, 0xffff0000, v72
	v_pk_add_f32 v[74:75], v[74:75], v[76:77]
	v_lshlrev_b32_e32 v76, 16, v66
	v_and_b32_e32 v77, 0xffff0000, v66
	v_and_b32_e32 v79, 0xffff0000, v68
	v_lshlrev_b32_e32 v70, 16, v71
	v_and_b32_e32 v71, 0xffff0000, v71
	v_lshlrev_b32_e32 v72, 16, v73
	v_and_b32_e32 v73, 0xffff0000, v73
	v_lshlrev_b32_e32 v66, 16, v67
	v_and_b32_e32 v67, 0xffff0000, v67
	v_lshlrev_b32_e32 v68, 16, v69
	v_and_b32_e32 v69, 0xffff0000, v69
	v_pk_add_f32 v[76:77], v[76:77], v[78:79]
	v_pk_add_f32 v[70:71], v[70:71], v[72:73]
	v_pk_add_f32 v[66:67], v[66:67], v[68:69]
	v_pk_add_f32 v[204:205], v[74:75], v[76:77]
	v_pk_add_f32 v[206:207], v[70:71], v[66:67]
	v_pk_add_f32 v[154:155], v[114:115], v[154:155]
	v_pk_mul_f32 v[194:195], v[170:171], v[170:171]
	v_pk_mul_f32 v[196:197], v[172:173], v[172:173]
	v_pk_mul_f32 v[208:209], v[204:205], v[204:205]
	v_pk_mul_f32 v[210:211], v[206:207], v[206:207]
	v_lshl_add_u64 v[120:121], v[64:65], 0, s[14:15]
	v_lshl_add_u64 v[122:123], v[64:65], 0, s[16:17]
	v_lshl_add_u64 v[64:65], v[120:121], 0, v[132:133]
	v_lshl_add_u64 v[68:69], v[122:123], 0, v[132:133]
	v_lshl_add_u64 v[72:73], v[120:121], 0, v[140:141]
	v_lshl_add_u64 v[76:77], v[122:123], 0, v[140:141]
	v_lshl_add_u64 v[80:81], v[120:121], 0, v[142:143]
	v_lshl_add_u64 v[84:85], v[122:123], 0, v[142:143]
	v_lshl_add_u64 v[88:89], v[120:121], 0, v[144:145]
	v_lshl_add_u64 v[92:93], v[122:123], 0, v[144:145]
	v_lshl_add_u64 v[96:97], v[120:121], 0, v[146:147]
	v_lshl_add_u64 v[100:101], v[122:123], 0, v[146:147]
	v_lshl_add_u64 v[104:105], v[120:121], 0, v[148:149]
	v_lshl_add_u64 v[108:109], v[122:123], 0, v[148:149]
	v_lshl_add_u64 v[112:113], v[120:121], 0, v[150:151]
	v_lshl_add_u64 v[116:117], v[122:123], 0, v[150:151]
	v_lshl_add_u64 v[120:121], v[120:121], 0, v[152:153]
	v_lshl_add_u64 v[124:125], v[122:123], 0, v[152:153]
	global_load_dwordx4 v[64:67], v[64:65], off
	s_nop 0
	global_load_dwordx4 v[68:71], v[68:69], off
	s_nop 0
	global_load_dwordx4 v[72:75], v[72:73], off
	s_nop 0
	global_load_dwordx4 v[76:79], v[76:77], off
	s_nop 0
	global_load_dwordx4 v[80:83], v[80:81], off
	s_nop 0
	global_load_dwordx4 v[84:87], v[84:85], off
	s_nop 0
	global_load_dwordx4 v[88:91], v[88:89], off
	s_nop 0
	global_load_dwordx4 v[92:95], v[92:93], off
	s_nop 0
	global_load_dwordx4 v[96:99], v[96:97], off
	s_nop 0
	global_load_dwordx4 v[100:103], v[100:101], off
	s_nop 0
	global_load_dwordx4 v[104:107], v[104:105], off
	s_nop 0
	global_load_dwordx4 v[108:111], v[108:109], off
	s_nop 0
	global_load_dwordx4 v[112:115], v[112:113], off
	s_nop 0
	global_load_dwordx4 v[116:119], v[116:117], off
	s_nop 0
	global_load_dwordx4 v[120:123], v[120:121], off
	s_nop 0
	global_load_dwordx4 v[124:127], v[124:125], off
	v_mov_b32_e32 v216, v157
	v_mov_b32_e32 v217, v161
	v_mov_b32_e32 v212, v155
	v_mov_b32_e32 v213, v159
	v_mov_b32_e32 v214, v156
	v_mov_b32_e32 v215, v160
	v_pk_mul_f32 v[216:217], v[216:217], v[216:217]
	v_pk_mul_f32 v[212:213], v[212:213], v[212:213]
	v_pk_fma_f32 v[214:215], v[214:215], v[214:215], v[216:217]
	v_mov_b32_e32 v216, v154
	v_mov_b32_e32 v217, v158
	v_pk_fma_f32 v[212:213], v[216:217], v[216:217], v[212:213]
	v_mov_b32_e32 v191, v196
	v_pk_add_f32 v[212:213], v[212:213], v[214:215]
	v_mov_b32_e32 v193, v197
	v_pk_add_f32 v[212:213], v[212:213], v[212:213] op_sel:[0,1] op_sel_hi:[1,0]
	v_mov_b32_e32 v177, v195
	v_mov_b32_e32 v213, v194
	v_pk_add_f32 v[190:191], v[190:191], v[192:193]
	v_pk_add_f32 v[176:177], v[212:213], v[176:177]
	v_mov_b32_e32 v201, v210
	v_pk_add_f32 v[176:177], v[176:177], v[190:191]
	v_mov_b32_e32 v203, v211
	v_pk_add_f32 v[176:177], v[176:177], v[176:177] op_sel:[0,1] op_sel_hi:[1,0]
	v_mov_b32_e32 v199, v209
	v_mov_b32_e32 v177, v208
	v_pk_add_f32 v[190:191], v[200:201], v[202:203]
	v_pk_add_f32 v[176:177], v[176:177], v[198:199]
	s_nop 0
	v_pk_add_f32 v[176:177], v[176:177], v[190:191]
	s_nop 0
	v_add_f32_e32 v176, v176, v177
	ds_bpermute_b32 v177, v129, v176
	s_waitcnt lgkmcnt(0)
	v_add_f32_e32 v176, v176, v177
	ds_bpermute_b32 v177, v184, v176
	s_waitcnt lgkmcnt(0)
	v_add_f32_e32 v176, v176, v177
	ds_bpermute_b32 v177, v185, v176
	s_waitcnt lgkmcnt(0)
	v_add_f32_e32 v176, v176, v177
	ds_bpermute_b32 v177, v186, v176
	s_waitcnt lgkmcnt(0)
	v_add_f32_e32 v176, v176, v177
	ds_bpermute_b32 v177, v187, v176
	s_waitcnt lgkmcnt(0)
	v_add_f32_e32 v176, v176, v177
	ds_bpermute_b32 v177, v188, v176
	s_waitcnt lgkmcnt(0)
	v_add_f32_e32 v176, v176, v177
	v_fmamk_f32 v176, v176, 0x3a000000, v131
	v_mul_f32_e32 v177, 0x4b800000, v176
	v_cmp_gt_f32_e32 vcc, s22, v176
	s_nop 1
	v_cndmask_b32_e32 v176, v176, v177, vcc
	v_rsq_f32_e32 v176, v176
	s_nop 0
	v_mul_f32_e32 v177, 0x45800000, v176
	v_cndmask_b32_e32 v176, v176, v177, vcc
	v_pk_mul_f32 v[158:159], v[158:159], v[176:177] op_sel_hi:[1,0]
	v_pk_mul_f32 v[160:161], v[160:161], v[176:177] op_sel_hi:[1,0]
	v_pk_fma_f32 v[24:25], v[32:33], v[158:159], v[24:25]
	v_pk_fma_f32 v[26:27], v[34:35], v[160:161], v[26:27]
	v_pk_mul_f32 v[32:33], v[180:181], v[176:177] op_sel_hi:[1,0]
	v_pk_mul_f32 v[34:35], v[182:183], v[176:177] op_sel_hi:[1,0]
	v_pk_mul_f32 v[154:155], v[154:155], v[176:177] op_sel_hi:[1,0]
	v_pk_mul_f32 v[156:157], v[156:157], v[176:177] op_sel_hi:[1,0]
	s_waitcnt vmcnt(17)
	v_pk_fma_f32 v[6:7], v[62:63], v[34:35], v[6:7]
	v_pk_fma_f32 v[4:5], v[60:61], v[32:33], v[4:5]
	v_pk_mul_f32 v[32:33], v[204:205], v[176:177] op_sel_hi:[1,0]
	v_pk_mul_f32 v[34:35], v[206:207], v[176:177] op_sel_hi:[1,0]
	v_pk_mul_f32 v[162:163], v[162:163], v[176:177] op_sel_hi:[1,0]
	v_pk_mul_f32 v[164:165], v[164:165], v[176:177] op_sel_hi:[1,0]
	v_pk_mul_f32 v[166:167], v[166:167], v[176:177] op_sel_hi:[1,0]
	v_pk_mul_f32 v[168:169], v[168:169], v[176:177] op_sel_hi:[1,0]
	v_pk_mul_f32 v[170:171], v[170:171], v[176:177] op_sel_hi:[1,0]
	v_pk_mul_f32 v[172:173], v[172:173], v[176:177] op_sel_hi:[1,0]
	v_pk_mul_f32 v[174:175], v[174:175], v[176:177] op_sel_hi:[1,0]
	v_pk_mul_f32 v[178:179], v[178:179], v[176:177] op_sel_hi:[1,0]
	v_pk_fma_f32 v[30:31], v[38:39], v[156:157], v[30:31]
	v_pk_fma_f32 v[28:29], v[36:37], v[154:155], v[28:29]
	s_waitcnt vmcnt(16)
	v_pk_fma_f32 v[2:3], v[50:51], v[34:35], v[2:3]
	v_pk_fma_f32 v[0:1], v[48:49], v[32:33], v[0:1]
	v_pk_fma_f32 v[22:23], v[46:47], v[164:165], v[22:23]
	v_pk_fma_f32 v[20:21], v[44:45], v[162:163], v[20:21]
	v_pk_fma_f32 v[18:19], v[42:43], v[168:169], v[18:19]
	v_pk_fma_f32 v[16:17], v[40:41], v[166:167], v[16:17]
	v_pk_fma_f32 v[14:15], v[58:59], v[172:173], v[14:15]
	v_pk_fma_f32 v[12:13], v[56:57], v[170:171], v[12:13]
	v_pk_fma_f32 v[10:11], v[54:55], v[178:179], v[10:11]
	v_pk_fma_f32 v[8:9], v[52:53], v[174:175], v[8:9]
	global_store_dwordx4 v[136:137], v[28:31], off offset:-4096 nt
	global_store_dwordx4 v[136:137], v[24:27], off offset:-3072 nt
	global_store_dwordx4 v[136:137], v[20:23], off offset:-2048 nt
	global_store_dwordx4 v[136:137], v[16:19], off offset:-1024 nt
	global_store_dwordx4 v[136:137], v[12:15], off nt
	global_store_dwordx4 v[136:137], v[8:11], off offset:1024 nt
	global_store_dwordx4 v[136:137], v[4:7], off offset:2048 nt
	global_store_dwordx4 v[136:137], v[0:3], off offset:3072 nt
	v_mov_b32_e32 v34, v29
	v_mov_b32_e32 v35, v25
	v_mov_b32_e32 v38, v31
	v_mov_b32_e32 v39, v27
	v_mov_b32_e32 v32, v28
	v_mov_b32_e32 v33, v24
	v_mov_b32_e32 v36, v30
	v_mov_b32_e32 v37, v26
	v_pk_mul_f32 v[40:41], v[22:23], v[22:23]
	v_pk_mul_f32 v[42:43], v[20:21], v[20:21]
	v_pk_mul_f32 v[34:35], v[34:35], v[34:35]
	v_pk_mul_f32 v[38:39], v[38:39], v[38:39]
	v_pk_mov_b32 v[58:59], v[42:43], v[40:41] op_sel:[1,0]
	v_mov_b32_e32 v43, v41
	v_pk_fma_f32 v[32:33], v[32:33], v[32:33], v[34:35]
	v_pk_fma_f32 v[34:35], v[36:37], v[36:37], v[38:39]
	v_mul_f32_e32 v44, v16, v16
	v_mul_f32_e32 v46, v18, v18
	v_pk_add_f32 v[36:37], v[58:59], v[42:43]
	v_pk_add_f32 v[32:33], v[32:33], v[34:35]
	v_pk_fma_f32 v[40:41], v[16:17], v[16:17], v[44:45] op_sel_hi:[1,1,0]
	v_pk_fma_f32 v[44:45], v[18:19], v[18:19], v[46:47] op_sel_hi:[1,1,0]
	v_pk_add_f32 v[34:35], v[36:37], v[36:37] op_sel_hi:[0,1]
	v_pk_add_f32 v[32:33], v[32:33], v[32:33] op_sel_hi:[0,1]
	v_pk_mul_f32 v[48:49], v[10:11], v[10:11]
	v_pk_mul_f32 v[50:51], v[8:9], v[8:9]
	v_mul_f32_e32 v40, v12, v12
	v_mul_f32_e32 v44, v13, v13
	v_mul_f32_e32 v34, v14, v14
	v_mul_f32_e32 v32, v15, v15
	v_pk_mov_b32 v[46:47], v[50:51], v[48:49] op_sel:[1,0]
	v_mov_b32_e32 v51, v49
	v_pk_add_f32 v[36:37], v[40:41], v[44:45]
	v_pk_add_f32 v[32:33], v[34:35], v[32:33]
	v_mul_f32_e32 v52, v4, v4
	v_mul_f32_e32 v54, v6, v6
	v_pk_add_f32 v[38:39], v[46:47], v[50:51]
	v_pk_add_f32 v[32:33], v[36:37], v[32:33]
	v_pk_fma_f32 v[48:49], v[4:5], v[4:5], v[52:53] op_sel_hi:[1,1,0]
	v_pk_fma_f32 v[52:53], v[6:7], v[6:7], v[54:55] op_sel_hi:[1,1,0]
	v_pk_add_f32 v[38:39], v[38:39], v[38:39] op_sel_hi:[0,1]
	v_pk_add_f32 v[32:33], v[32:33], v[32:33] op_sel_hi:[0,1]
	v_mul_f32_e32 v48, v0, v0
	v_mul_f32_e32 v52, v1, v1
	v_mul_f32_e32 v38, v2, v2
	v_mul_f32_e32 v32, v3, v3
	v_pk_add_f32 v[40:41], v[48:49], v[52:53]
	v_pk_add_f32 v[32:33], v[38:39], v[32:33]
	v_add_co_u32_e32 v56, vcc, s23, v134
	v_pk_add_f32 v[32:33], v[40:41], v[32:33]
	s_nop 0
	v_addc_co_u32_e32 v57, vcc, -1, v135, vcc
	v_add_f32_e32 v32, v32, v33
	ds_bpermute_b32 v33, v129, v32
	v_readfirstlane_b32 s83, v237
	s_lshl_b32 s83, s83, 1
	s_add_u32 s83, s83, s86
	s_add_u32 s83, s83, s94
	s_lshl_b32 s83, s83, 3
	s_sub_u32 s84, s83, s82
	s_mov_b32 s82, s83
	s_mov_b32 s85, 0
	s_mov_b32 s2, s84
	s_lshl_b64 s[6:7], s[84:85], 12
	s_lshl_b64 s[8:9], s[84:85], 13
	v_add_u32_e32 v130, s2, v130
	v_cmp_lt_i32_e32 vcc, s24, v130
	s_or_b64 s[10:11], vcc, s[10:11]
	v_lshl_add_u64 v[134:135], v[134:135], 0, s[6:7]
	s_waitcnt lgkmcnt(0)
	v_add_f32_e32 v32, v32, v33
	ds_bpermute_b32 v33, v184, v32
	v_lshl_add_u64 v[136:137], v[136:137], 0, s[8:9]
	s_waitcnt lgkmcnt(0)
	v_add_f32_e32 v32, v32, v33
	ds_bpermute_b32 v33, v185, v32
	s_waitcnt lgkmcnt(0)
	v_add_f32_e32 v32, v32, v33
	ds_bpermute_b32 v33, v186, v32
	s_waitcnt lgkmcnt(0)
	v_add_f32_e32 v32, v32, v33
	ds_bpermute_b32 v33, v187, v32
	s_waitcnt lgkmcnt(0)
	v_add_f32_e32 v32, v32, v33
	ds_bpermute_b32 v33, v188, v32
	s_waitcnt lgkmcnt(0)
	v_add_f32_e32 v32, v32, v33
	v_fmamk_f32 v32, v32, 0x3a000000, v131
	v_mul_f32_e32 v33, 0x4b800000, v32
	v_cmp_gt_f32_e32 vcc, s22, v32
	s_nop 1
	v_cndmask_b32_e32 v32, v32, v33, vcc
	v_rsq_f32_e32 v32, v32
	s_nop 0
	v_mul_f32_e32 v33, 0x45800000, v32
	v_cndmask_b32_e32 v32, v32, v33, vcc
	v_pk_mul_f32 v[28:29], v[28:29], v[32:33] op_sel_hi:[1,0]
	v_pk_mul_f32 v[30:31], v[30:31], v[32:33] op_sel_hi:[1,0]
	v_pk_mul_f32 v[24:25], v[24:25], v[32:33] op_sel_hi:[1,0]
	v_pk_mul_f32 v[26:27], v[26:27], v[32:33] op_sel_hi:[1,0]
	v_pk_mul_f32 v[20:21], v[20:21], v[32:33] op_sel_hi:[1,0]
	v_pk_mul_f32 v[22:23], v[22:23], v[32:33] op_sel_hi:[1,0]
	v_pk_mul_f32 v[16:17], v[16:17], v[32:33] op_sel_hi:[1,0]
	v_pk_mul_f32 v[18:19], v[18:19], v[32:33] op_sel_hi:[1,0]
	v_pk_mul_f32 v[12:13], v[12:13], v[32:33] op_sel_hi:[1,0]
	v_pk_mul_f32 v[14:15], v[14:15], v[32:33] op_sel_hi:[1,0]
	v_pk_mul_f32 v[8:9], v[8:9], v[32:33] op_sel_hi:[1,0]
	v_pk_mul_f32 v[10:11], v[10:11], v[32:33] op_sel_hi:[1,0]
	v_pk_mul_f32 v[4:5], v[4:5], v[32:33] op_sel_hi:[1,0]
	v_pk_mul_f32 v[6:7], v[6:7], v[32:33] op_sel_hi:[1,0]
	v_pk_mul_f32 v[0:1], v[0:1], v[32:33] op_sel_hi:[1,0]
	v_pk_mul_f32 v[2:3], v[2:3], v[32:33] op_sel_hi:[1,0]
	s_waitcnt vmcnt(22)
	v_pk_fma_f32 v[30:31], v[66:67], v[30:31], v[70:71]
	v_pk_fma_f32 v[28:29], v[64:65], v[28:29], v[68:69]
	s_waitcnt vmcnt(20)
	v_pk_fma_f32 v[26:27], v[74:75], v[26:27], v[78:79]
	v_pk_fma_f32 v[24:25], v[72:73], v[24:25], v[76:77]
	s_waitcnt vmcnt(18)
	v_pk_fma_f32 v[22:23], v[82:83], v[22:23], v[86:87]
	v_pk_fma_f32 v[20:21], v[80:81], v[20:21], v[84:85]
	s_waitcnt vmcnt(16)
	v_pk_fma_f32 v[18:19], v[90:91], v[18:19], v[94:95]
	v_pk_fma_f32 v[16:17], v[88:89], v[16:17], v[92:93]
	s_waitcnt vmcnt(14)
	v_pk_fma_f32 v[14:15], v[98:99], v[14:15], v[102:103]
	v_pk_fma_f32 v[12:13], v[96:97], v[12:13], v[100:101]
	s_waitcnt vmcnt(12)
	v_pk_fma_f32 v[10:11], v[106:107], v[10:11], v[110:111]
	v_pk_fma_f32 v[8:9], v[104:105], v[8:9], v[108:109]
	s_waitcnt vmcnt(10)
	v_pk_fma_f32 v[6:7], v[114:115], v[6:7], v[118:119]
	v_pk_fma_f32 v[4:5], v[112:113], v[4:5], v[116:117]
	s_waitcnt vmcnt(8)
	v_pk_fma_f32 v[2:3], v[122:123], v[2:3], v[126:127]
	v_pk_fma_f32 v[0:1], v[120:121], v[0:1], v[124:125]
	v_cvt_pk_bf16_f32 v28, v28, v29
	v_cvt_pk_bf16_f32 v29, v30, v31
	v_cvt_pk_bf16_f32 v24, v24, v25
	v_cvt_pk_bf16_f32 v25, v26, v27
	v_cvt_pk_bf16_f32 v20, v20, v21
	v_cvt_pk_bf16_f32 v21, v22, v23
	v_cvt_pk_bf16_f32 v16, v16, v17
	v_cvt_pk_bf16_f32 v17, v18, v19
	v_cvt_pk_bf16_f32 v12, v12, v13
	v_cvt_pk_bf16_f32 v13, v14, v15
	v_cvt_pk_bf16_f32 v8, v8, v9
	v_cvt_pk_bf16_f32 v9, v10, v11
	v_cvt_pk_bf16_f32 v4, v4, v5
	v_cvt_pk_bf16_f32 v5, v6, v7
	v_cvt_pk_bf16_f32 v0, v0, v1
	v_cvt_pk_bf16_f32 v1, v2, v3
	global_store_dwordx2 v[56:57], v[28:29], off offset:-3584
	global_store_dwordx2 v[56:57], v[24:25], off offset:-3072
	global_store_dwordx2 v[56:57], v[20:21], off offset:-2560
	global_store_dwordx2 v[56:57], v[16:17], off offset:-2048
	global_store_dwordx2 v[56:57], v[12:13], off offset:-1536
	global_store_dwordx2 v[56:57], v[8:9], off offset:-1024
	global_store_dwordx2 v[56:57], v[4:5], off offset:-512
	global_store_dwordx2 v[56:57], v[0:1], off
	s_andn2_b64 exec, exec, s[10:11]
	s_cbranch_execnz .LBB0_1625
